# NSA selected-branch tile loop: all 8 K-fragment LDS reads issued up front and all 8 V^T reads at PV start with counted lgkmcnt (was serialized read->wait->2 MFMA), on top of scan v2b
# speedup vs baseline: 1.0025x; 1.0025x over previous
; #define LAS __attribute__((address_space(3)))
; __device__ __forceinline__ void scan_phase(const Args& a, LAS unsigned char* lds, int tid, int lane, int wave, int G, int bid) {
;     ...
;             LAS float* buf = OP + (ch & 1) * SC_CH * SC_STEP;
;             if (stager) { SCAN_PUT8(buf + ldP, rKK); SCAN_PUT8(buf + ldP + 64, rAK); SCAN_PUT8(buf + ldP + 192, rK); SCAN_PUT8(buf + ldP + 256, rR);
;                 *(LAS f32x4*)(buf + ldD) = rD0; *(LAS f32x4*)(buf + ldD + 16 * SC_STEP) = rD1;
;                 if (sid < 64) { LAS float* vd = VV + (ch & 1) * 512 + (vst >> 2) * 64 + (vhalf * 8) * 4 + (vst & 3); vd[0] = bf_lo(rV.x); vd[4] = bf_hi(rV.x); vd[8] = bf_lo(rV.y); vd[12] = bf_hi(rV.y); vd[16] = bf_lo(rV.z); vd[20] = bf_hi(rV.z); vd[24] = bf_lo(rV.w); vd[28] = bf_hi(rV.w); } }
;             __syncthreads();
;             if (ch + 1 < SEQ / SC_CH) SCAN_ISSUE(ch + 1);
;             if (wave < 4) {
;                 const LAS float* op0 = buf + 4 * c; const LAS float* vv0 = VV + (ch & 1) * 512 + row * 4;
;                 f32x4 nkk = *(const LAS f32x4*)(op0), nak = *(const LAS f32x4*)(op0 + 64), nw = *(const LAS f32x4*)(op0 + 128), nk = *(const LAS f32x4*)(op0 + 192), nr = *(const LAS f32x4*)(op0 + 256);
;                 f32x4 nv[4] = {*(const LAS f32x4*)(vv0), *(const LAS f32x4*)(vv0 + 64), *(const LAS f32x4*)(vv0 + 128), *(const LAS f32x4*)(vv0 + 192)};
; #pragma unroll 1
;                 for (int oh = 0; oh < 2; ++oh) {
;                     const LAS float* opb = op0 + oh * 16 * SC_STEP;
;                     const f32x4 vq[4] = {nv[0], nv[1], nv[2], nv[3]};
;                     { const int ohn = oh < 1 ? 1 : 1;
; #pragma unroll
;                       for (int q = 0; q < 4; ++q) nv[q] = *(const LAS f32x4*)(vv0 + (ohn * 4 + q) * 64); }
;                     float yk = 0.f;
; #pragma unroll
;                     for (int i = 0; i < 16; ++i) {
;                         const f32x4 kk4 = nkk, ak4 = nak, w4 = nw, k4 = nk, r4 = nr; const float vv = vq[i >> 2][i & 3];
;                         { const int nx = (i < 15) ? (i + 1) : (oh < 1 ? 16 : 15); const LAS float* on = opb + nx * SC_STEP;
;                           nkk = *(const LAS f32x4*)(on); nak = *(const LAS f32x4*)(on + 64); nw = *(const LAS f32x4*)(on + 128); nk = *(const LAS f32x4*)(on + 192); nr = *(const LAS f32x4*)(on + 256); }
.Lsc_compute:
	s_and_b32 s15, s54, 1
	s_mul_i32 s23, s15, 0xa800
	v_add_u32_e32 v101, s23, v99
	v_lshl_add_u32 v103, s15, 11, v119
	v_lshl_add_u32 v146, s15, 11, v123
	ds_read_b128 v[76:79], v103 offset:0
	ds_read_b128 v[36:39], v101 offset:0
	ds_read_b128 v[40:43], v101 offset:256
	ds_read_b128 v[44:47], v101 offset:512
	ds_read_b128 v[48:51], v101 offset:768
	ds_read_b128 v[52:55], v101 offset:1024
	ds_read_b128 v[56:59], v101 offset:1344
	ds_read_b128 v[60:63], v101 offset:1600
	ds_read_b128 v[64:67], v101 offset:1856
	ds_read_b128 v[68:71], v101 offset:2112
	ds_read_b128 v[72:75], v101 offset:2368
	s_waitcnt lgkmcnt(5)
	v_pk_mul_f32 v[88:89], v[84:85], v[36:37]
	v_pk_fma_f32 v[88:89], v[86:87], v[38:39], v[88:89]
	v_add_f32_e32 v92, v88, v89
	s_nop 0
	v_pk_mul_f32 v[120:121], v[48:49], v[76:77] op_sel:[0,0] op_sel_hi:[1,0]
	v_add_f32_dpp v92, v92, v92 row_ror:8 row_mask:0xf bank_mask:0xf bound_ctrl:1
	s_nop 0
	v_pk_mul_f32 v[238:239], v[50:51], v[76:77] op_sel:[0,0] op_sel_hi:[1,0]
	v_add_f32_dpp v92, v92, v92 row_ror:4 row_mask:0xf bank_mask:0xf bound_ctrl:1
	s_nop 0
	v_pk_fma_f32 v[240:241], v[84:85], v[44:45], v[120:121]
	v_add_f32_dpp v92, v92, v92 row_ror:2 row_mask:0xf bank_mask:0xf bound_ctrl:1
	s_nop 0
	v_pk_fma_f32 v[242:243], v[86:87], v[46:47], v[238:239]
	v_add_f32_dpp v92, v92, v92 row_ror:1 row_mask:0xf bank_mask:0xf bound_ctrl:1
	v_pk_fma_f32 v[84:85], v[92:93], v[40:41], v[240:241] op_sel_hi:[0,1,1] neg_lo:[1,0,0] neg_hi:[1,0,0]
	v_pk_fma_f32 v[86:87], v[92:93], v[42:43], v[242:243] op_sel_hi:[0,1,1] neg_lo:[1,0,0] neg_hi:[1,0,0]
	ds_read_b128 v[148:151], v101 offset:2688
	ds_read_b128 v[152:155], v101 offset:2944
	ds_read_b128 v[156:159], v101 offset:3200
	ds_read_b128 v[160:163], v101 offset:3456
	ds_read_b128 v[164:167], v101 offset:3712
	s_waitcnt lgkmcnt(5)
	v_pk_mul_f32 v[88:89], v[84:85], v[56:57]
	v_pk_mul_f32 v[90:91], v[84:85], v[52:53]
	v_pk_fma_f32 v[88:89], v[86:87], v[58:59], v[88:89]
	v_pk_fma_f32 v[90:91], v[86:87], v[54:55], v[90:91]
	v_add_f32_e32 v92, v88, v89
	v_add_f32_e32 v118, v90, v91
	v_pk_mul_f32 v[120:121], v[68:69], v[76:77] op_sel:[0,1] op_sel_hi:[1,1]
	v_add_f32_dpp v92, v92, v92 row_ror:8 row_mask:0xf bank_mask:0xf bound_ctrl:1
	v_add_f32_dpp v118, v118, v118 row_ror:8 row_mask:0xf bank_mask:0xf bound_ctrl:1
	v_pk_mul_f32 v[238:239], v[70:71], v[76:77] op_sel:[0,1] op_sel_hi:[1,1]
	v_add_f32_dpp v92, v92, v92 row_ror:4 row_mask:0xf bank_mask:0xf bound_ctrl:1
	v_add_f32_dpp v118, v118, v118 row_ror:4 row_mask:0xf bank_mask:0xf bound_ctrl:1
	v_pk_fma_f32 v[240:241], v[84:85], v[64:65], v[120:121]
	v_add_f32_dpp v92, v92, v92 row_ror:2 row_mask:0xf bank_mask:0xf bound_ctrl:1
	v_add_f32_dpp v118, v118, v118 row_ror:2 row_mask:0xf bank_mask:0xf bound_ctrl:1
	v_pk_fma_f32 v[242:243], v[86:87], v[66:67], v[238:239]
	v_add_f32_dpp v92, v92, v92 row_ror:1 row_mask:0xf bank_mask:0xf bound_ctrl:1
	v_add_f32_dpp v118, v118, v118 row_ror:1 row_mask:0xf bank_mask:0xf bound_ctrl:1
	v_pk_fma_f32 v[84:85], v[92:93], v[60:61], v[240:241] op_sel_hi:[0,1,1] neg_lo:[1,0,0] neg_hi:[1,0,0]
	v_pk_fma_f32 v[86:87], v[92:93], v[62:63], v[242:243] op_sel_hi:[0,1,1] neg_lo:[1,0,0] neg_hi:[1,0,0]
	v_mul_f32_e32 v145, v127, v118
	ds_read_b128 v[168:171], v101 offset:4032
	ds_read_b128 v[172:175], v101 offset:4288
	ds_read_b128 v[176:179], v101 offset:4544
	ds_read_b128 v[180:183], v101 offset:4800
	ds_read_b128 v[184:187], v101 offset:5056
	ds_read_b128 v[80:83], v103 offset:256
	s_waitcnt lgkmcnt(6)
	v_pk_mul_f32 v[88:89], v[84:85], v[148:149]
	v_pk_mul_f32 v[90:91], v[84:85], v[72:73]
	v_pk_fma_f32 v[88:89], v[86:87], v[150:151], v[88:89]
	v_pk_fma_f32 v[90:91], v[86:87], v[74:75], v[90:91]
	v_add_f32_e32 v92, v88, v89
	v_add_f32_e32 v118, v90, v91
	v_pk_mul_f32 v[120:121], v[160:161], v[78:79] op_sel:[0,0] op_sel_hi:[1,0]
	v_add_f32_dpp v92, v92, v92 row_ror:8 row_mask:0xf bank_mask:0xf bound_ctrl:1
	v_add_f32_dpp v118, v118, v118 row_ror:8 row_mask:0xf bank_mask:0xf bound_ctrl:1
	v_pk_mul_f32 v[238:239], v[162:163], v[78:79] op_sel:[0,0] op_sel_hi:[1,0]
	v_add_f32_dpp v92, v92, v92 row_ror:4 row_mask:0xf bank_mask:0xf bound_ctrl:1
	v_add_f32_dpp v118, v118, v118 row_ror:4 row_mask:0xf bank_mask:0xf bound_ctrl:1
	v_pk_fma_f32 v[240:241], v[84:85], v[156:157], v[120:121]
	v_add_f32_dpp v92, v92, v92 row_ror:2 row_mask:0xf bank_mask:0xf bound_ctrl:1
	v_add_f32_dpp v118, v118, v118 row_ror:2 row_mask:0xf bank_mask:0xf bound_ctrl:1
	v_pk_fma_f32 v[242:243], v[86:87], v[158:159], v[238:239]
	v_add_f32_dpp v92, v92, v92 row_ror:1 row_mask:0xf bank_mask:0xf bound_ctrl:1
	v_add_f32_dpp v118, v118, v118 row_ror:1 row_mask:0xf bank_mask:0xf bound_ctrl:1
	v_pk_fma_f32 v[84:85], v[92:93], v[152:153], v[240:241] op_sel_hi:[0,1,1] neg_lo:[1,0,0] neg_hi:[1,0,0]
	v_pk_fma_f32 v[86:87], v[92:93], v[154:155], v[242:243] op_sel_hi:[0,1,1] neg_lo:[1,0,0] neg_hi:[1,0,0]
	v_fmac_f32_e32 v145, v129, v118
	ds_read_b128 v[36:39], v101 offset:5376
	ds_read_b128 v[40:43], v101 offset:5632
	ds_read_b128 v[44:47], v101 offset:5888
	ds_read_b128 v[48:51], v101 offset:6144
	ds_read_b128 v[52:55], v101 offset:6400
	s_waitcnt lgkmcnt(6)
; #define LAS __attribute__((address_space(3)))
; __device__ __forceinline__ float allred16_dpp(float x) { x = dpp_add<0x128>(x); x = dpp_add<0x124>(x); x = dpp_add<0x122>(x); x = dpp_add<0x121>(x); return x; }
; __device__ __forceinline__ void scan_phase(const Args& a, LAS unsigned char* lds, int tid, int lane, int wave, int G, int bid) {
;     ...
;                     for (int i = 0; i < 16; ++i) {
;                         const f32x4 kk4 = nkk, ak4 = nak, w4 = nw, k4 = nk, r4 = nr; const float vv = vq[i >> 2][i & 3];
;                         { const int nx = (i < 15) ? (i + 1) : (oh < 1 ? 16 : 15); const LAS float* on = opb + nx * SC_STEP;
;                           nkk = *(const LAS f32x4*)(on); nak = *(const LAS f32x4*)(on + 64); nw = *(const LAS f32x4*)(on + 128); nk = *(const LAS f32x4*)(on + 192); nr = *(const LAS f32x4*)(on + 256); }
;                         f32x2 t = Sa * (f32x2){kk4[0], kk4[1]}; t = __builtin_elementwise_fma(Sb, (f32x2){kk4[2], kk4[3]}, t);
;                         float sa = t.x + t.y;
;                         sa = allred16_dpp(sa);
;                         const f32x2 nsa2 = (f32x2){-sa, -sa}, vv2 = (f32x2){vv, vv};
;                         f32x2 ua = vv2 * (f32x2){k4[0], k4[1]}, ub = vv2 * (f32x2){k4[2], k4[3]};
;                         ua = __builtin_elementwise_fma(nsa2, (f32x2){ak4[0], ak4[1]}, ua); ub = __builtin_elementwise_fma(nsa2, (f32x2){ak4[2], ak4[3]}, ub);
;                         Sa = __builtin_elementwise_fma(Sa, (f32x2){w4[0], w4[1]}, ua); Sb = __builtin_elementwise_fma(Sb, (f32x2){w4[2], w4[3]}, ub);
;                         f32x2 yy = Sa * (f32x2){r4[0], r4[1]}; yy = __builtin_elementwise_fma(Sb, (f32x2){r4[2], r4[3]}, yy);
;                         float y = yy.x + yy.y;
;                         y = allred16_dpp(y);
;                         yk = fmaf(wsel[i], y, yk);
	v_pk_mul_f32 v[88:89], v[84:85], v[168:169]
	v_pk_mul_f32 v[90:91], v[84:85], v[164:165]
	v_pk_fma_f32 v[88:89], v[86:87], v[170:171], v[88:89]
	v_pk_fma_f32 v[90:91], v[86:87], v[166:167], v[90:91]
	v_add_f32_e32 v92, v88, v89
	v_add_f32_e32 v118, v90, v91
	v_pk_mul_f32 v[120:121], v[180:181], v[78:79] op_sel:[0,1] op_sel_hi:[1,1]
	v_add_f32_dpp v92, v92, v92 row_ror:8 row_mask:0xf bank_mask:0xf bound_ctrl:1
	v_add_f32_dpp v118, v118, v118 row_ror:8 row_mask:0xf bank_mask:0xf bound_ctrl:1
	v_pk_mul_f32 v[238:239], v[182:183], v[78:79] op_sel:[0,1] op_sel_hi:[1,1]
	v_add_f32_dpp v92, v92, v92 row_ror:4 row_mask:0xf bank_mask:0xf bound_ctrl:1
	v_add_f32_dpp v118, v118, v118 row_ror:4 row_mask:0xf bank_mask:0xf bound_ctrl:1
	v_pk_fma_f32 v[240:241], v[84:85], v[176:177], v[120:121]
	v_add_f32_dpp v92, v92, v92 row_ror:2 row_mask:0xf bank_mask:0xf bound_ctrl:1
	v_add_f32_dpp v118, v118, v118 row_ror:2 row_mask:0xf bank_mask:0xf bound_ctrl:1
	v_pk_fma_f32 v[242:243], v[86:87], v[178:179], v[238:239]
	v_add_f32_dpp v92, v92, v92 row_ror:1 row_mask:0xf bank_mask:0xf bound_ctrl:1
	v_add_f32_dpp v118, v118, v118 row_ror:1 row_mask:0xf bank_mask:0xf bound_ctrl:1
	v_pk_fma_f32 v[84:85], v[92:93], v[172:173], v[240:241] op_sel_hi:[0,1,1] neg_lo:[1,0,0] neg_hi:[1,0,0]
	v_pk_fma_f32 v[86:87], v[92:93], v[174:175], v[242:243] op_sel_hi:[0,1,1] neg_lo:[1,0,0] neg_hi:[1,0,0]
	v_fmac_f32_e32 v145, v131, v118
	ds_read_b128 v[56:59], v101 offset:6720
	ds_read_b128 v[60:63], v101 offset:6976
	ds_read_b128 v[64:67], v101 offset:7232
	ds_read_b128 v[68:71], v101 offset:7488
	ds_read_b128 v[72:75], v101 offset:7744
	s_waitcnt lgkmcnt(5)
	v_pk_mul_f32 v[88:89], v[84:85], v[36:37]
	v_pk_mul_f32 v[90:91], v[84:85], v[184:185]
	v_pk_fma_f32 v[88:89], v[86:87], v[38:39], v[88:89]
	v_pk_fma_f32 v[90:91], v[86:87], v[186:187], v[90:91]
	v_add_f32_e32 v92, v88, v89
	v_add_f32_e32 v118, v90, v91
	v_pk_mul_f32 v[120:121], v[48:49], v[80:81] op_sel:[0,0] op_sel_hi:[1,0]
	v_add_f32_dpp v92, v92, v92 row_ror:8 row_mask:0xf bank_mask:0xf bound_ctrl:1
	v_add_f32_dpp v118, v118, v118 row_ror:8 row_mask:0xf bank_mask:0xf bound_ctrl:1
	v_pk_mul_f32 v[238:239], v[50:51], v[80:81] op_sel:[0,0] op_sel_hi:[1,0]
	v_add_f32_dpp v92, v92, v92 row_ror:4 row_mask:0xf bank_mask:0xf bound_ctrl:1
	v_add_f32_dpp v118, v118, v118 row_ror:4 row_mask:0xf bank_mask:0xf bound_ctrl:1
	v_pk_fma_f32 v[240:241], v[84:85], v[44:45], v[120:121]
	v_add_f32_dpp v92, v92, v92 row_ror:2 row_mask:0xf bank_mask:0xf bound_ctrl:1
	v_add_f32_dpp v118, v118, v118 row_ror:2 row_mask:0xf bank_mask:0xf bound_ctrl:1
	v_pk_fma_f32 v[242:243], v[86:87], v[46:47], v[238:239]
	v_add_f32_dpp v92, v92, v92 row_ror:1 row_mask:0xf bank_mask:0xf bound_ctrl:1
	v_add_f32_dpp v118, v118, v118 row_ror:1 row_mask:0xf bank_mask:0xf bound_ctrl:1
	v_pk_fma_f32 v[84:85], v[92:93], v[40:41], v[240:241] op_sel_hi:[0,1,1] neg_lo:[1,0,0] neg_hi:[1,0,0]
	v_pk_fma_f32 v[86:87], v[92:93], v[42:43], v[242:243] op_sel_hi:[0,1,1] neg_lo:[1,0,0] neg_hi:[1,0,0]
	v_fmac_f32_e32 v145, v132, v118
	ds_read_b128 v[148:151], v101 offset:8064
	ds_read_b128 v[152:155], v101 offset:8320
	ds_read_b128 v[156:159], v101 offset:8576
	ds_read_b128 v[160:163], v101 offset:8832
	ds_read_b128 v[164:167], v101 offset:9088
	s_waitcnt lgkmcnt(5)
	v_pk_mul_f32 v[88:89], v[84:85], v[56:57]
	v_pk_mul_f32 v[90:91], v[84:85], v[52:53]
	v_pk_fma_f32 v[88:89], v[86:87], v[58:59], v[88:89]
	v_pk_fma_f32 v[90:91], v[86:87], v[54:55], v[90:91]
	v_add_f32_e32 v92, v88, v89
	v_add_f32_e32 v118, v90, v91
	v_pk_mul_f32 v[120:121], v[68:69], v[80:81] op_sel:[0,1] op_sel_hi:[1,1]
	v_add_f32_dpp v92, v92, v92 row_ror:8 row_mask:0xf bank_mask:0xf bound_ctrl:1
	v_add_f32_dpp v118, v118, v118 row_ror:8 row_mask:0xf bank_mask:0xf bound_ctrl:1
	v_pk_mul_f32 v[238:239], v[70:71], v[80:81] op_sel:[0,1] op_sel_hi:[1,1]
	v_add_f32_dpp v92, v92, v92 row_ror:4 row_mask:0xf bank_mask:0xf bound_ctrl:1
	v_add_f32_dpp v118, v118, v118 row_ror:4 row_mask:0xf bank_mask:0xf bound_ctrl:1
	v_pk_fma_f32 v[240:241], v[84:85], v[64:65], v[120:121]
	v_add_f32_dpp v92, v92, v92 row_ror:2 row_mask:0xf bank_mask:0xf bound_ctrl:1
	v_add_f32_dpp v118, v118, v118 row_ror:2 row_mask:0xf bank_mask:0xf bound_ctrl:1
	v_pk_fma_f32 v[242:243], v[86:87], v[66:67], v[238:239]
	v_add_f32_dpp v92, v92, v92 row_ror:1 row_mask:0xf bank_mask:0xf bound_ctrl:1
	v_add_f32_dpp v118, v118, v118 row_ror:1 row_mask:0xf bank_mask:0xf bound_ctrl:1
	v_pk_fma_f32 v[84:85], v[92:93], v[60:61], v[240:241] op_sel_hi:[0,1,1] neg_lo:[1,0,0] neg_hi:[1,0,0]
	v_pk_fma_f32 v[86:87], v[92:93], v[62:63], v[242:243] op_sel_hi:[0,1,1] neg_lo:[1,0,0] neg_hi:[1,0,0]
	v_fmac_f32_e32 v145, v133, v118
	ds_read_b128 v[168:171], v101 offset:9408
	ds_read_b128 v[172:175], v101 offset:9664
	ds_read_b128 v[176:179], v101 offset:9920
	ds_read_b128 v[180:183], v101 offset:10176
	ds_read_b128 v[184:187], v101 offset:10432
	ds_read_b128 v[76:79], v103 offset:512
	s_waitcnt lgkmcnt(6)
; #define LAS __attribute__((address_space(3)))
; __device__ __forceinline__ float allred16_dpp(float x) { x = dpp_add<0x128>(x); x = dpp_add<0x124>(x); x = dpp_add<0x122>(x); x = dpp_add<0x121>(x); return x; }
; __device__ __forceinline__ void scan_phase(const Args& a, LAS unsigned char* lds, int tid, int lane, int wave, int G, int bid) {
;     ...
;                     for (int i = 0; i < 16; ++i) {
;                         const f32x4 kk4 = nkk, ak4 = nak, w4 = nw, k4 = nk, r4 = nr; const float vv = vq[i >> 2][i & 3];
;                         { const int nx = (i < 15) ? (i + 1) : (oh < 1 ? 16 : 15); const LAS float* on = opb + nx * SC_STEP;
;                           nkk = *(const LAS f32x4*)(on); nak = *(const LAS f32x4*)(on + 64); nw = *(const LAS f32x4*)(on + 128); nk = *(const LAS f32x4*)(on + 192); nr = *(const LAS f32x4*)(on + 256); }
;                         f32x2 t = Sa * (f32x2){kk4[0], kk4[1]}; t = __builtin_elementwise_fma(Sb, (f32x2){kk4[2], kk4[3]}, t);
;                         float sa = t.x + t.y;
;                         sa = allred16_dpp(sa);
;                         const f32x2 nsa2 = (f32x2){-sa, -sa}, vv2 = (f32x2){vv, vv};
;                         f32x2 ua = vv2 * (f32x2){k4[0], k4[1]}, ub = vv2 * (f32x2){k4[2], k4[3]};
;                         ua = __builtin_elementwise_fma(nsa2, (f32x2){ak4[0], ak4[1]}, ua); ub = __builtin_elementwise_fma(nsa2, (f32x2){ak4[2], ak4[3]}, ub);
;                         Sa = __builtin_elementwise_fma(Sa, (f32x2){w4[0], w4[1]}, ua); Sb = __builtin_elementwise_fma(Sb, (f32x2){w4[2], w4[3]}, ub);
;                         f32x2 yy = Sa * (f32x2){r4[0], r4[1]}; yy = __builtin_elementwise_fma(Sb, (f32x2){r4[2], r4[3]}, yy);
;                         float y = yy.x + yy.y;
;                         y = allred16_dpp(y);
;                         yk = fmaf(wsel[i], y, yk);
	v_pk_mul_f32 v[88:89], v[84:85], v[148:149]
	v_pk_mul_f32 v[90:91], v[84:85], v[72:73]
	v_pk_fma_f32 v[88:89], v[86:87], v[150:151], v[88:89]
	v_pk_fma_f32 v[90:91], v[86:87], v[74:75], v[90:91]
	v_add_f32_e32 v92, v88, v89
	v_add_f32_e32 v118, v90, v91
	v_pk_mul_f32 v[120:121], v[160:161], v[82:83] op_sel:[0,0] op_sel_hi:[1,0]
	v_add_f32_dpp v92, v92, v92 row_ror:8 row_mask:0xf bank_mask:0xf bound_ctrl:1
	v_add_f32_dpp v118, v118, v118 row_ror:8 row_mask:0xf bank_mask:0xf bound_ctrl:1
	v_pk_mul_f32 v[238:239], v[162:163], v[82:83] op_sel:[0,0] op_sel_hi:[1,0]
	v_add_f32_dpp v92, v92, v92 row_ror:4 row_mask:0xf bank_mask:0xf bound_ctrl:1
	v_add_f32_dpp v118, v118, v118 row_ror:4 row_mask:0xf bank_mask:0xf bound_ctrl:1
	v_pk_fma_f32 v[240:241], v[84:85], v[156:157], v[120:121]
	v_add_f32_dpp v92, v92, v92 row_ror:2 row_mask:0xf bank_mask:0xf bound_ctrl:1
	v_add_f32_dpp v118, v118, v118 row_ror:2 row_mask:0xf bank_mask:0xf bound_ctrl:1
	v_pk_fma_f32 v[242:243], v[86:87], v[158:159], v[238:239]
	v_add_f32_dpp v92, v92, v92 row_ror:1 row_mask:0xf bank_mask:0xf bound_ctrl:1
	v_add_f32_dpp v118, v118, v118 row_ror:1 row_mask:0xf bank_mask:0xf bound_ctrl:1
	v_pk_fma_f32 v[84:85], v[92:93], v[152:153], v[240:241] op_sel_hi:[0,1,1] neg_lo:[1,0,0] neg_hi:[1,0,0]
	v_pk_fma_f32 v[86:87], v[92:93], v[154:155], v[242:243] op_sel_hi:[0,1,1] neg_lo:[1,0,0] neg_hi:[1,0,0]
	v_fmac_f32_e32 v145, v134, v118
	ds_read_b128 v[36:39], v101 offset:10752
	ds_read_b128 v[40:43], v101 offset:11008
	ds_read_b128 v[44:47], v101 offset:11264
	ds_read_b128 v[48:51], v101 offset:11520
	ds_read_b128 v[52:55], v101 offset:11776
	s_waitcnt lgkmcnt(6)
	v_pk_mul_f32 v[88:89], v[84:85], v[168:169]
	v_pk_mul_f32 v[90:91], v[84:85], v[164:165]
	v_pk_fma_f32 v[88:89], v[86:87], v[170:171], v[88:89]
	v_pk_fma_f32 v[90:91], v[86:87], v[166:167], v[90:91]
	v_add_f32_e32 v92, v88, v89
	v_add_f32_e32 v118, v90, v91
	v_pk_mul_f32 v[120:121], v[180:181], v[82:83] op_sel:[0,1] op_sel_hi:[1,1]
	v_add_f32_dpp v92, v92, v92 row_ror:8 row_mask:0xf bank_mask:0xf bound_ctrl:1
	v_add_f32_dpp v118, v118, v118 row_ror:8 row_mask:0xf bank_mask:0xf bound_ctrl:1
	v_pk_mul_f32 v[238:239], v[182:183], v[82:83] op_sel:[0,1] op_sel_hi:[1,1]
	v_add_f32_dpp v92, v92, v92 row_ror:4 row_mask:0xf bank_mask:0xf bound_ctrl:1
	v_add_f32_dpp v118, v118, v118 row_ror:4 row_mask:0xf bank_mask:0xf bound_ctrl:1
	v_pk_fma_f32 v[240:241], v[84:85], v[176:177], v[120:121]
	v_add_f32_dpp v92, v92, v92 row_ror:2 row_mask:0xf bank_mask:0xf bound_ctrl:1
	v_add_f32_dpp v118, v118, v118 row_ror:2 row_mask:0xf bank_mask:0xf bound_ctrl:1
	v_pk_fma_f32 v[242:243], v[86:87], v[178:179], v[238:239]
	v_add_f32_dpp v92, v92, v92 row_ror:1 row_mask:0xf bank_mask:0xf bound_ctrl:1
	v_add_f32_dpp v118, v118, v118 row_ror:1 row_mask:0xf bank_mask:0xf bound_ctrl:1
	v_pk_fma_f32 v[84:85], v[92:93], v[172:173], v[240:241] op_sel_hi:[0,1,1] neg_lo:[1,0,0] neg_hi:[1,0,0]
	v_pk_fma_f32 v[86:87], v[92:93], v[174:175], v[242:243] op_sel_hi:[0,1,1] neg_lo:[1,0,0] neg_hi:[1,0,0]
	v_fmac_f32_e32 v145, v135, v118
	ds_read_b128 v[56:59], v101 offset:12096
	ds_read_b128 v[60:63], v101 offset:12352
	ds_read_b128 v[64:67], v101 offset:12608
	ds_read_b128 v[68:71], v101 offset:12864
	ds_read_b128 v[72:75], v101 offset:13120
	s_waitcnt lgkmcnt(5)
	v_pk_mul_f32 v[88:89], v[84:85], v[36:37]
	v_pk_mul_f32 v[90:91], v[84:85], v[184:185]
	v_pk_fma_f32 v[88:89], v[86:87], v[38:39], v[88:89]
	v_pk_fma_f32 v[90:91], v[86:87], v[186:187], v[90:91]
	v_add_f32_e32 v92, v88, v89
	v_add_f32_e32 v118, v90, v91
	v_pk_mul_f32 v[120:121], v[48:49], v[76:77] op_sel:[0,0] op_sel_hi:[1,0]
	v_add_f32_dpp v92, v92, v92 row_ror:8 row_mask:0xf bank_mask:0xf bound_ctrl:1
	v_add_f32_dpp v118, v118, v118 row_ror:8 row_mask:0xf bank_mask:0xf bound_ctrl:1
	v_pk_mul_f32 v[238:239], v[50:51], v[76:77] op_sel:[0,0] op_sel_hi:[1,0]
	v_add_f32_dpp v92, v92, v92 row_ror:4 row_mask:0xf bank_mask:0xf bound_ctrl:1
	v_add_f32_dpp v118, v118, v118 row_ror:4 row_mask:0xf bank_mask:0xf bound_ctrl:1
	v_pk_fma_f32 v[240:241], v[84:85], v[44:45], v[120:121]
	v_add_f32_dpp v92, v92, v92 row_ror:2 row_mask:0xf bank_mask:0xf bound_ctrl:1
	v_add_f32_dpp v118, v118, v118 row_ror:2 row_mask:0xf bank_mask:0xf bound_ctrl:1
	v_pk_fma_f32 v[242:243], v[86:87], v[46:47], v[238:239]
	v_add_f32_dpp v92, v92, v92 row_ror:1 row_mask:0xf bank_mask:0xf bound_ctrl:1
	v_add_f32_dpp v118, v118, v118 row_ror:1 row_mask:0xf bank_mask:0xf bound_ctrl:1
	v_pk_fma_f32 v[84:85], v[92:93], v[40:41], v[240:241] op_sel_hi:[0,1,1] neg_lo:[1,0,0] neg_hi:[1,0,0]
	v_pk_fma_f32 v[86:87], v[92:93], v[42:43], v[242:243] op_sel_hi:[0,1,1] neg_lo:[1,0,0] neg_hi:[1,0,0]
	v_fmac_f32_e32 v145, v136, v118
	ds_read_b128 v[148:151], v101 offset:13440
	ds_read_b128 v[152:155], v101 offset:13696
	ds_read_b128 v[156:159], v101 offset:13952
	ds_read_b128 v[160:163], v101 offset:14208
	ds_read_b128 v[164:167], v101 offset:14464
	s_waitcnt lgkmcnt(5)
; #define LAS __attribute__((address_space(3)))
; __device__ __forceinline__ float allred16_dpp(float x) { x = dpp_add<0x128>(x); x = dpp_add<0x124>(x); x = dpp_add<0x122>(x); x = dpp_add<0x121>(x); return x; }
; __device__ __forceinline__ void scan_phase(const Args& a, LAS unsigned char* lds, int tid, int lane, int wave, int G, int bid) {
;     ...
;                     for (int i = 0; i < 16; ++i) {
;                         const f32x4 kk4 = nkk, ak4 = nak, w4 = nw, k4 = nk, r4 = nr; const float vv = vq[i >> 2][i & 3];
;                         { const int nx = (i < 15) ? (i + 1) : (oh < 1 ? 16 : 15); const LAS float* on = opb + nx * SC_STEP;
;                           nkk = *(const LAS f32x4*)(on); nak = *(const LAS f32x4*)(on + 64); nw = *(const LAS f32x4*)(on + 128); nk = *(const LAS f32x4*)(on + 192); nr = *(const LAS f32x4*)(on + 256); }
;                         f32x2 t = Sa * (f32x2){kk4[0], kk4[1]}; t = __builtin_elementwise_fma(Sb, (f32x2){kk4[2], kk4[3]}, t);
;                         float sa = t.x + t.y;
;                         sa = allred16_dpp(sa);
;                         const f32x2 nsa2 = (f32x2){-sa, -sa}, vv2 = (f32x2){vv, vv};
;                         f32x2 ua = vv2 * (f32x2){k4[0], k4[1]}, ub = vv2 * (f32x2){k4[2], k4[3]};
;                         ua = __builtin_elementwise_fma(nsa2, (f32x2){ak4[0], ak4[1]}, ua); ub = __builtin_elementwise_fma(nsa2, (f32x2){ak4[2], ak4[3]}, ub);
;                         Sa = __builtin_elementwise_fma(Sa, (f32x2){w4[0], w4[1]}, ua); Sb = __builtin_elementwise_fma(Sb, (f32x2){w4[2], w4[3]}, ub);
;                         f32x2 yy = Sa * (f32x2){r4[0], r4[1]}; yy = __builtin_elementwise_fma(Sb, (f32x2){r4[2], r4[3]}, yy);
;                         float y = yy.x + yy.y;
;                         y = allred16_dpp(y);
;                         yk = fmaf(wsel[i], y, yk);
	v_pk_mul_f32 v[88:89], v[84:85], v[56:57]
	v_pk_mul_f32 v[90:91], v[84:85], v[52:53]
	v_pk_fma_f32 v[88:89], v[86:87], v[58:59], v[88:89]
	v_pk_fma_f32 v[90:91], v[86:87], v[54:55], v[90:91]
	v_add_f32_e32 v92, v88, v89
	v_add_f32_e32 v118, v90, v91
	v_pk_mul_f32 v[120:121], v[68:69], v[76:77] op_sel:[0,1] op_sel_hi:[1,1]
	v_add_f32_dpp v92, v92, v92 row_ror:8 row_mask:0xf bank_mask:0xf bound_ctrl:1
	v_add_f32_dpp v118, v118, v118 row_ror:8 row_mask:0xf bank_mask:0xf bound_ctrl:1
	v_pk_mul_f32 v[238:239], v[70:71], v[76:77] op_sel:[0,1] op_sel_hi:[1,1]
	v_add_f32_dpp v92, v92, v92 row_ror:4 row_mask:0xf bank_mask:0xf bound_ctrl:1
	v_add_f32_dpp v118, v118, v118 row_ror:4 row_mask:0xf bank_mask:0xf bound_ctrl:1
	v_pk_fma_f32 v[240:241], v[84:85], v[64:65], v[120:121]
	v_add_f32_dpp v92, v92, v92 row_ror:2 row_mask:0xf bank_mask:0xf bound_ctrl:1
	v_add_f32_dpp v118, v118, v118 row_ror:2 row_mask:0xf bank_mask:0xf bound_ctrl:1
	v_pk_fma_f32 v[242:243], v[86:87], v[66:67], v[238:239]
	v_add_f32_dpp v92, v92, v92 row_ror:1 row_mask:0xf bank_mask:0xf bound_ctrl:1
	v_add_f32_dpp v118, v118, v118 row_ror:1 row_mask:0xf bank_mask:0xf bound_ctrl:1
	v_pk_fma_f32 v[84:85], v[92:93], v[60:61], v[240:241] op_sel_hi:[0,1,1] neg_lo:[1,0,0] neg_hi:[1,0,0]
	v_pk_fma_f32 v[86:87], v[92:93], v[62:63], v[242:243] op_sel_hi:[0,1,1] neg_lo:[1,0,0] neg_hi:[1,0,0]
	v_fmac_f32_e32 v145, v137, v118
	ds_read_b128 v[168:171], v101 offset:14784
	ds_read_b128 v[172:175], v101 offset:15040
	ds_read_b128 v[176:179], v101 offset:15296
	ds_read_b128 v[180:183], v101 offset:15552
	ds_read_b128 v[184:187], v101 offset:15808
	ds_read_b128 v[80:83], v103 offset:768
	s_waitcnt lgkmcnt(6)
	v_pk_mul_f32 v[88:89], v[84:85], v[148:149]
	v_pk_mul_f32 v[90:91], v[84:85], v[72:73]
	v_pk_fma_f32 v[88:89], v[86:87], v[150:151], v[88:89]
	v_pk_fma_f32 v[90:91], v[86:87], v[74:75], v[90:91]
	v_add_f32_e32 v92, v88, v89
	v_add_f32_e32 v118, v90, v91
	v_pk_mul_f32 v[120:121], v[160:161], v[78:79] op_sel:[0,0] op_sel_hi:[1,0]
	v_add_f32_dpp v92, v92, v92 row_ror:8 row_mask:0xf bank_mask:0xf bound_ctrl:1
	v_add_f32_dpp v118, v118, v118 row_ror:8 row_mask:0xf bank_mask:0xf bound_ctrl:1
	v_pk_mul_f32 v[238:239], v[162:163], v[78:79] op_sel:[0,0] op_sel_hi:[1,0]
	v_add_f32_dpp v92, v92, v92 row_ror:4 row_mask:0xf bank_mask:0xf bound_ctrl:1
	v_add_f32_dpp v118, v118, v118 row_ror:4 row_mask:0xf bank_mask:0xf bound_ctrl:1
	v_pk_fma_f32 v[240:241], v[84:85], v[156:157], v[120:121]
	v_add_f32_dpp v92, v92, v92 row_ror:2 row_mask:0xf bank_mask:0xf bound_ctrl:1
	v_add_f32_dpp v118, v118, v118 row_ror:2 row_mask:0xf bank_mask:0xf bound_ctrl:1
	v_pk_fma_f32 v[242:243], v[86:87], v[158:159], v[238:239]
	v_add_f32_dpp v92, v92, v92 row_ror:1 row_mask:0xf bank_mask:0xf bound_ctrl:1
	v_add_f32_dpp v118, v118, v118 row_ror:1 row_mask:0xf bank_mask:0xf bound_ctrl:1
	v_pk_fma_f32 v[84:85], v[92:93], v[152:153], v[240:241] op_sel_hi:[0,1,1] neg_lo:[1,0,0] neg_hi:[1,0,0]
	v_pk_fma_f32 v[86:87], v[92:93], v[154:155], v[242:243] op_sel_hi:[0,1,1] neg_lo:[1,0,0] neg_hi:[1,0,0]
	v_fmac_f32_e32 v145, v138, v118
	ds_read_b128 v[36:39], v101 offset:16128
	ds_read_b128 v[40:43], v101 offset:16384
	ds_read_b128 v[44:47], v101 offset:16640
	ds_read_b128 v[48:51], v101 offset:16896
	ds_read_b128 v[52:55], v101 offset:17152
	s_waitcnt lgkmcnt(6)
	v_pk_mul_f32 v[88:89], v[84:85], v[168:169]
	v_pk_mul_f32 v[90:91], v[84:85], v[164:165]
	v_pk_fma_f32 v[88:89], v[86:87], v[170:171], v[88:89]
	v_pk_fma_f32 v[90:91], v[86:87], v[166:167], v[90:91]
	v_add_f32_e32 v92, v88, v89
	v_add_f32_e32 v118, v90, v91
	v_pk_mul_f32 v[120:121], v[180:181], v[78:79] op_sel:[0,1] op_sel_hi:[1,1]
	v_add_f32_dpp v92, v92, v92 row_ror:8 row_mask:0xf bank_mask:0xf bound_ctrl:1
	v_add_f32_dpp v118, v118, v118 row_ror:8 row_mask:0xf bank_mask:0xf bound_ctrl:1
	v_pk_mul_f32 v[238:239], v[182:183], v[78:79] op_sel:[0,1] op_sel_hi:[1,1]
	v_add_f32_dpp v92, v92, v92 row_ror:4 row_mask:0xf bank_mask:0xf bound_ctrl:1
	v_add_f32_dpp v118, v118, v118 row_ror:4 row_mask:0xf bank_mask:0xf bound_ctrl:1
	v_pk_fma_f32 v[240:241], v[84:85], v[176:177], v[120:121]
	v_add_f32_dpp v92, v92, v92 row_ror:2 row_mask:0xf bank_mask:0xf bound_ctrl:1
	v_add_f32_dpp v118, v118, v118 row_ror:2 row_mask:0xf bank_mask:0xf bound_ctrl:1
	v_pk_fma_f32 v[242:243], v[86:87], v[178:179], v[238:239]
	v_add_f32_dpp v92, v92, v92 row_ror:1 row_mask:0xf bank_mask:0xf bound_ctrl:1
	v_add_f32_dpp v118, v118, v118 row_ror:1 row_mask:0xf bank_mask:0xf bound_ctrl:1
	v_pk_fma_f32 v[84:85], v[92:93], v[172:173], v[240:241] op_sel_hi:[0,1,1] neg_lo:[1,0,0] neg_hi:[1,0,0]
	v_pk_fma_f32 v[86:87], v[92:93], v[174:175], v[242:243] op_sel_hi:[0,1,1] neg_lo:[1,0,0] neg_hi:[1,0,0]
	v_fmac_f32_e32 v145, v139, v118
	ds_read_b128 v[56:59], v101 offset:17472
	ds_read_b128 v[60:63], v101 offset:17728
	ds_read_b128 v[64:67], v101 offset:17984
	ds_read_b128 v[68:71], v101 offset:18240
	ds_read_b128 v[72:75], v101 offset:18496
	s_waitcnt lgkmcnt(5)
; #define LAS __attribute__((address_space(3)))
; __device__ __forceinline__ float allred16_dpp(float x) { x = dpp_add<0x128>(x); x = dpp_add<0x124>(x); x = dpp_add<0x122>(x); x = dpp_add<0x121>(x); return x; }
; __device__ __forceinline__ void scan_phase(const Args& a, LAS unsigned char* lds, int tid, int lane, int wave, int G, int bid) {
;     ...
;                     for (int i = 0; i < 16; ++i) {
;                         const f32x4 kk4 = nkk, ak4 = nak, w4 = nw, k4 = nk, r4 = nr; const float vv = vq[i >> 2][i & 3];
;                         { const int nx = (i < 15) ? (i + 1) : (oh < 1 ? 16 : 15); const LAS float* on = opb + nx * SC_STEP;
;                           nkk = *(const LAS f32x4*)(on); nak = *(const LAS f32x4*)(on + 64); nw = *(const LAS f32x4*)(on + 128); nk = *(const LAS f32x4*)(on + 192); nr = *(const LAS f32x4*)(on + 256); }
;                         f32x2 t = Sa * (f32x2){kk4[0], kk4[1]}; t = __builtin_elementwise_fma(Sb, (f32x2){kk4[2], kk4[3]}, t);
;                         float sa = t.x + t.y;
;                         sa = allred16_dpp(sa);
;                         const f32x2 nsa2 = (f32x2){-sa, -sa}, vv2 = (f32x2){vv, vv};
;                         f32x2 ua = vv2 * (f32x2){k4[0], k4[1]}, ub = vv2 * (f32x2){k4[2], k4[3]};
;                         ua = __builtin_elementwise_fma(nsa2, (f32x2){ak4[0], ak4[1]}, ua); ub = __builtin_elementwise_fma(nsa2, (f32x2){ak4[2], ak4[3]}, ub);
;                         Sa = __builtin_elementwise_fma(Sa, (f32x2){w4[0], w4[1]}, ua); Sb = __builtin_elementwise_fma(Sb, (f32x2){w4[2], w4[3]}, ub);
;                         f32x2 yy = Sa * (f32x2){r4[0], r4[1]}; yy = __builtin_elementwise_fma(Sb, (f32x2){r4[2], r4[3]}, yy);
;                         float y = yy.x + yy.y;
;                         y = allred16_dpp(y);
;                         yk = fmaf(wsel[i], y, yk);
	v_pk_mul_f32 v[88:89], v[84:85], v[36:37]
	v_pk_mul_f32 v[90:91], v[84:85], v[184:185]
	v_pk_fma_f32 v[88:89], v[86:87], v[38:39], v[88:89]
	v_pk_fma_f32 v[90:91], v[86:87], v[186:187], v[90:91]
	v_add_f32_e32 v92, v88, v89
	v_add_f32_e32 v118, v90, v91
	v_pk_mul_f32 v[120:121], v[48:49], v[80:81] op_sel:[0,0] op_sel_hi:[1,0]
	v_add_f32_dpp v92, v92, v92 row_ror:8 row_mask:0xf bank_mask:0xf bound_ctrl:1
	v_add_f32_dpp v118, v118, v118 row_ror:8 row_mask:0xf bank_mask:0xf bound_ctrl:1
	v_pk_mul_f32 v[238:239], v[50:51], v[80:81] op_sel:[0,0] op_sel_hi:[1,0]
	v_add_f32_dpp v92, v92, v92 row_ror:4 row_mask:0xf bank_mask:0xf bound_ctrl:1
	v_add_f32_dpp v118, v118, v118 row_ror:4 row_mask:0xf bank_mask:0xf bound_ctrl:1
	v_pk_fma_f32 v[240:241], v[84:85], v[44:45], v[120:121]
	v_add_f32_dpp v92, v92, v92 row_ror:2 row_mask:0xf bank_mask:0xf bound_ctrl:1
	v_add_f32_dpp v118, v118, v118 row_ror:2 row_mask:0xf bank_mask:0xf bound_ctrl:1
	v_pk_fma_f32 v[242:243], v[86:87], v[46:47], v[238:239]
	v_add_f32_dpp v92, v92, v92 row_ror:1 row_mask:0xf bank_mask:0xf bound_ctrl:1
	v_add_f32_dpp v118, v118, v118 row_ror:1 row_mask:0xf bank_mask:0xf bound_ctrl:1
	v_pk_fma_f32 v[84:85], v[92:93], v[40:41], v[240:241] op_sel_hi:[0,1,1] neg_lo:[1,0,0] neg_hi:[1,0,0]
	v_pk_fma_f32 v[86:87], v[92:93], v[42:43], v[242:243] op_sel_hi:[0,1,1] neg_lo:[1,0,0] neg_hi:[1,0,0]
	v_fmac_f32_e32 v145, v140, v118
	ds_read_b128 v[148:151], v101 offset:18816
	ds_read_b128 v[152:155], v101 offset:19072
	ds_read_b128 v[156:159], v101 offset:19328
	ds_read_b128 v[160:163], v101 offset:19584
	ds_read_b128 v[164:167], v101 offset:19840
	s_waitcnt lgkmcnt(5)
	v_pk_mul_f32 v[88:89], v[84:85], v[56:57]
	v_pk_mul_f32 v[90:91], v[84:85], v[52:53]
	v_pk_fma_f32 v[88:89], v[86:87], v[58:59], v[88:89]
	v_pk_fma_f32 v[90:91], v[86:87], v[54:55], v[90:91]
	v_add_f32_e32 v92, v88, v89
	v_add_f32_e32 v118, v90, v91
	v_pk_mul_f32 v[120:121], v[68:69], v[80:81] op_sel:[0,1] op_sel_hi:[1,1]
	v_add_f32_dpp v92, v92, v92 row_ror:8 row_mask:0xf bank_mask:0xf bound_ctrl:1
	v_add_f32_dpp v118, v118, v118 row_ror:8 row_mask:0xf bank_mask:0xf bound_ctrl:1
	v_pk_mul_f32 v[238:239], v[70:71], v[80:81] op_sel:[0,1] op_sel_hi:[1,1]
	v_add_f32_dpp v92, v92, v92 row_ror:4 row_mask:0xf bank_mask:0xf bound_ctrl:1
	v_add_f32_dpp v118, v118, v118 row_ror:4 row_mask:0xf bank_mask:0xf bound_ctrl:1
	v_pk_fma_f32 v[240:241], v[84:85], v[64:65], v[120:121]
	v_add_f32_dpp v92, v92, v92 row_ror:2 row_mask:0xf bank_mask:0xf bound_ctrl:1
	v_add_f32_dpp v118, v118, v118 row_ror:2 row_mask:0xf bank_mask:0xf bound_ctrl:1
	v_pk_fma_f32 v[242:243], v[86:87], v[66:67], v[238:239]
	v_add_f32_dpp v92, v92, v92 row_ror:1 row_mask:0xf bank_mask:0xf bound_ctrl:1
	v_add_f32_dpp v118, v118, v118 row_ror:1 row_mask:0xf bank_mask:0xf bound_ctrl:1
	v_pk_fma_f32 v[84:85], v[92:93], v[60:61], v[240:241] op_sel_hi:[0,1,1] neg_lo:[1,0,0] neg_hi:[1,0,0]
	v_pk_fma_f32 v[86:87], v[92:93], v[62:63], v[242:243] op_sel_hi:[0,1,1] neg_lo:[1,0,0] neg_hi:[1,0,0]
	v_fmac_f32_e32 v145, v141, v118
	ds_read_b128 v[168:171], v101 offset:20160
	ds_read_b128 v[172:175], v101 offset:20416
	ds_read_b128 v[176:179], v101 offset:20672
	ds_read_b128 v[180:183], v101 offset:20928
	ds_read_b128 v[184:187], v101 offset:21184
	ds_read_b128 v[76:79], v103 offset:1024
	s_waitcnt lgkmcnt(6)
	v_pk_mul_f32 v[88:89], v[84:85], v[148:149]
	v_pk_mul_f32 v[90:91], v[84:85], v[72:73]
	v_pk_fma_f32 v[88:89], v[86:87], v[150:151], v[88:89]
	v_pk_fma_f32 v[90:91], v[86:87], v[74:75], v[90:91]
	v_add_f32_e32 v92, v88, v89
	v_add_f32_e32 v118, v90, v91
	v_pk_mul_f32 v[120:121], v[160:161], v[82:83] op_sel:[0,0] op_sel_hi:[1,0]
	v_add_f32_dpp v92, v92, v92 row_ror:8 row_mask:0xf bank_mask:0xf bound_ctrl:1
	v_add_f32_dpp v118, v118, v118 row_ror:8 row_mask:0xf bank_mask:0xf bound_ctrl:1
	v_pk_mul_f32 v[238:239], v[162:163], v[82:83] op_sel:[0,0] op_sel_hi:[1,0]
	v_add_f32_dpp v92, v92, v92 row_ror:4 row_mask:0xf bank_mask:0xf bound_ctrl:1
	v_add_f32_dpp v118, v118, v118 row_ror:4 row_mask:0xf bank_mask:0xf bound_ctrl:1
	v_pk_fma_f32 v[240:241], v[84:85], v[156:157], v[120:121]
	v_add_f32_dpp v92, v92, v92 row_ror:2 row_mask:0xf bank_mask:0xf bound_ctrl:1
	v_add_f32_dpp v118, v118, v118 row_ror:2 row_mask:0xf bank_mask:0xf bound_ctrl:1
	v_pk_fma_f32 v[242:243], v[86:87], v[158:159], v[238:239]
	v_add_f32_dpp v92, v92, v92 row_ror:1 row_mask:0xf bank_mask:0xf bound_ctrl:1
	v_add_f32_dpp v118, v118, v118 row_ror:1 row_mask:0xf bank_mask:0xf bound_ctrl:1
	v_pk_fma_f32 v[84:85], v[92:93], v[152:153], v[240:241] op_sel_hi:[0,1,1] neg_lo:[1,0,0] neg_hi:[1,0,0]
	v_pk_fma_f32 v[86:87], v[92:93], v[154:155], v[242:243] op_sel_hi:[0,1,1] neg_lo:[1,0,0] neg_hi:[1,0,0]
	v_fmac_f32_e32 v145, v142, v118
	ds_read_b128 v[36:39], v101 offset:21504
	ds_read_b128 v[40:43], v101 offset:21760
	ds_read_b128 v[44:47], v101 offset:22016
	ds_read_b128 v[48:51], v101 offset:22272
	ds_read_b128 v[52:55], v101 offset:22528
	s_waitcnt lgkmcnt(6)
; #define LAS __attribute__((address_space(3)))
; __device__ __forceinline__ float allred16_dpp(float x) { x = dpp_add<0x128>(x); x = dpp_add<0x124>(x); x = dpp_add<0x122>(x); x = dpp_add<0x121>(x); return x; }
; __device__ __forceinline__ void scan_phase(const Args& a, LAS unsigned char* lds, int tid, int lane, int wave, int G, int bid) {
;     ...
;                     for (int i = 0; i < 16; ++i) {
;                         const f32x4 kk4 = nkk, ak4 = nak, w4 = nw, k4 = nk, r4 = nr; const float vv = vq[i >> 2][i & 3];
;                         { const int nx = (i < 15) ? (i + 1) : (oh < 1 ? 16 : 15); const LAS float* on = opb + nx * SC_STEP;
;                           nkk = *(const LAS f32x4*)(on); nak = *(const LAS f32x4*)(on + 64); nw = *(const LAS f32x4*)(on + 128); nk = *(const LAS f32x4*)(on + 192); nr = *(const LAS f32x4*)(on + 256); }
;                         f32x2 t = Sa * (f32x2){kk4[0], kk4[1]}; t = __builtin_elementwise_fma(Sb, (f32x2){kk4[2], kk4[3]}, t);
;                         float sa = t.x + t.y;
;                         sa = allred16_dpp(sa);
;                         const f32x2 nsa2 = (f32x2){-sa, -sa}, vv2 = (f32x2){vv, vv};
;                         f32x2 ua = vv2 * (f32x2){k4[0], k4[1]}, ub = vv2 * (f32x2){k4[2], k4[3]};
;                         ua = __builtin_elementwise_fma(nsa2, (f32x2){ak4[0], ak4[1]}, ua); ub = __builtin_elementwise_fma(nsa2, (f32x2){ak4[2], ak4[3]}, ub);
;                         Sa = __builtin_elementwise_fma(Sa, (f32x2){w4[0], w4[1]}, ua); Sb = __builtin_elementwise_fma(Sb, (f32x2){w4[2], w4[3]}, ub);
;                         f32x2 yy = Sa * (f32x2){r4[0], r4[1]}; yy = __builtin_elementwise_fma(Sb, (f32x2){r4[2], r4[3]}, yy);
;                         float y = yy.x + yy.y;
;                         y = allred16_dpp(y);
;                         yk = fmaf(wsel[i], y, yk);
;                     }
;                     YB[(oh * 16 + c) * 16 + row] = yk;
	v_pk_mul_f32 v[88:89], v[84:85], v[168:169]
	v_pk_mul_f32 v[90:91], v[84:85], v[164:165]
	v_pk_fma_f32 v[88:89], v[86:87], v[170:171], v[88:89]
	v_pk_fma_f32 v[90:91], v[86:87], v[166:167], v[90:91]
	v_add_f32_e32 v92, v88, v89
	v_add_f32_e32 v118, v90, v91
	v_pk_mul_f32 v[120:121], v[180:181], v[82:83] op_sel:[0,1] op_sel_hi:[1,1]
	v_add_f32_dpp v92, v92, v92 row_ror:8 row_mask:0xf bank_mask:0xf bound_ctrl:1
	v_add_f32_dpp v118, v118, v118 row_ror:8 row_mask:0xf bank_mask:0xf bound_ctrl:1
	v_pk_mul_f32 v[238:239], v[182:183], v[82:83] op_sel:[0,1] op_sel_hi:[1,1]
	v_add_f32_dpp v92, v92, v92 row_ror:4 row_mask:0xf bank_mask:0xf bound_ctrl:1
	v_add_f32_dpp v118, v118, v118 row_ror:4 row_mask:0xf bank_mask:0xf bound_ctrl:1
	v_pk_fma_f32 v[240:241], v[84:85], v[176:177], v[120:121]
	v_add_f32_dpp v92, v92, v92 row_ror:2 row_mask:0xf bank_mask:0xf bound_ctrl:1
	v_add_f32_dpp v118, v118, v118 row_ror:2 row_mask:0xf bank_mask:0xf bound_ctrl:1
	v_pk_fma_f32 v[242:243], v[86:87], v[178:179], v[238:239]
	v_add_f32_dpp v92, v92, v92 row_ror:1 row_mask:0xf bank_mask:0xf bound_ctrl:1
	v_add_f32_dpp v118, v118, v118 row_ror:1 row_mask:0xf bank_mask:0xf bound_ctrl:1
	v_pk_fma_f32 v[84:85], v[92:93], v[172:173], v[240:241] op_sel_hi:[0,1,1] neg_lo:[1,0,0] neg_hi:[1,0,0]
	v_pk_fma_f32 v[86:87], v[92:93], v[174:175], v[242:243] op_sel_hi:[0,1,1] neg_lo:[1,0,0] neg_hi:[1,0,0]
	v_fmac_f32_e32 v145, v143, v118
	ds_read_b128 v[56:59], v101 offset:22848
	ds_read_b128 v[60:63], v101 offset:23104
	ds_read_b128 v[64:67], v101 offset:23360
	ds_read_b128 v[68:71], v101 offset:23616
	ds_read_b128 v[72:75], v101 offset:23872
	s_waitcnt lgkmcnt(5)
	v_pk_mul_f32 v[88:89], v[84:85], v[36:37]
	v_pk_mul_f32 v[90:91], v[84:85], v[184:185]
	v_pk_fma_f32 v[88:89], v[86:87], v[38:39], v[88:89]
	v_pk_fma_f32 v[90:91], v[86:87], v[186:187], v[90:91]
	v_add_f32_e32 v92, v88, v89
	v_add_f32_e32 v118, v90, v91
	v_pk_mul_f32 v[120:121], v[48:49], v[76:77] op_sel:[0,0] op_sel_hi:[1,0]
	v_add_f32_dpp v92, v92, v92 row_ror:8 row_mask:0xf bank_mask:0xf bound_ctrl:1
	v_add_f32_dpp v118, v118, v118 row_ror:8 row_mask:0xf bank_mask:0xf bound_ctrl:1
	v_pk_mul_f32 v[238:239], v[50:51], v[76:77] op_sel:[0,0] op_sel_hi:[1,0]
	v_add_f32_dpp v92, v92, v92 row_ror:4 row_mask:0xf bank_mask:0xf bound_ctrl:1
	v_add_f32_dpp v118, v118, v118 row_ror:4 row_mask:0xf bank_mask:0xf bound_ctrl:1
	v_pk_fma_f32 v[240:241], v[84:85], v[44:45], v[120:121]
	v_add_f32_dpp v92, v92, v92 row_ror:2 row_mask:0xf bank_mask:0xf bound_ctrl:1
	v_add_f32_dpp v118, v118, v118 row_ror:2 row_mask:0xf bank_mask:0xf bound_ctrl:1
	v_pk_fma_f32 v[242:243], v[86:87], v[46:47], v[238:239]
	v_add_f32_dpp v92, v92, v92 row_ror:1 row_mask:0xf bank_mask:0xf bound_ctrl:1
	v_add_f32_dpp v118, v118, v118 row_ror:1 row_mask:0xf bank_mask:0xf bound_ctrl:1
	v_pk_fma_f32 v[84:85], v[92:93], v[40:41], v[240:241] op_sel_hi:[0,1,1] neg_lo:[1,0,0] neg_hi:[1,0,0]
	v_pk_fma_f32 v[86:87], v[92:93], v[42:43], v[242:243] op_sel_hi:[0,1,1] neg_lo:[1,0,0] neg_hi:[1,0,0]
	v_fmac_f32_e32 v145, v144, v118
	ds_write_b32 v146, v145 offset:0
	ds_read_b128 v[148:151], v101 offset:24192
	ds_read_b128 v[152:155], v101 offset:24448
	ds_read_b128 v[156:159], v101 offset:24704
	ds_read_b128 v[160:163], v101 offset:24960
	ds_read_b128 v[164:167], v101 offset:25216
	s_waitcnt lgkmcnt(6)
	v_pk_mul_f32 v[88:89], v[84:85], v[56:57]
	v_pk_mul_f32 v[90:91], v[84:85], v[52:53]
	v_pk_fma_f32 v[88:89], v[86:87], v[58:59], v[88:89]
	v_pk_fma_f32 v[90:91], v[86:87], v[54:55], v[90:91]
	v_add_f32_e32 v92, v88, v89
	v_add_f32_e32 v118, v90, v91
	v_pk_mul_f32 v[120:121], v[68:69], v[76:77] op_sel:[0,1] op_sel_hi:[1,1]
	v_add_f32_dpp v92, v92, v92 row_ror:8 row_mask:0xf bank_mask:0xf bound_ctrl:1
	v_add_f32_dpp v118, v118, v118 row_ror:8 row_mask:0xf bank_mask:0xf bound_ctrl:1
	v_pk_mul_f32 v[238:239], v[70:71], v[76:77] op_sel:[0,1] op_sel_hi:[1,1]
	v_add_f32_dpp v92, v92, v92 row_ror:4 row_mask:0xf bank_mask:0xf bound_ctrl:1
	v_add_f32_dpp v118, v118, v118 row_ror:4 row_mask:0xf bank_mask:0xf bound_ctrl:1
	v_pk_fma_f32 v[240:241], v[84:85], v[64:65], v[120:121]
	v_add_f32_dpp v92, v92, v92 row_ror:2 row_mask:0xf bank_mask:0xf bound_ctrl:1
	v_add_f32_dpp v118, v118, v118 row_ror:2 row_mask:0xf bank_mask:0xf bound_ctrl:1
	v_pk_fma_f32 v[242:243], v[86:87], v[66:67], v[238:239]
	v_add_f32_dpp v92, v92, v92 row_ror:1 row_mask:0xf bank_mask:0xf bound_ctrl:1
	v_add_f32_dpp v118, v118, v118 row_ror:1 row_mask:0xf bank_mask:0xf bound_ctrl:1
	v_pk_fma_f32 v[84:85], v[92:93], v[60:61], v[240:241] op_sel_hi:[0,1,1] neg_lo:[1,0,0] neg_hi:[1,0,0]
	v_pk_fma_f32 v[86:87], v[92:93], v[62:63], v[242:243] op_sel_hi:[0,1,1] neg_lo:[1,0,0] neg_hi:[1,0,0]
	v_mul_f32_e32 v244, v127, v118
	ds_read_b128 v[168:171], v101 offset:25536
	ds_read_b128 v[172:175], v101 offset:25792
	ds_read_b128 v[176:179], v101 offset:26048
	ds_read_b128 v[180:183], v101 offset:26304
	ds_read_b128 v[184:187], v101 offset:26560
	ds_read_b128 v[80:83], v103 offset:1280
	s_waitcnt lgkmcnt(6)
; #define LAS __attribute__((address_space(3)))
; __device__ __forceinline__ float allred16_dpp(float x) { x = dpp_add<0x128>(x); x = dpp_add<0x124>(x); x = dpp_add<0x122>(x); x = dpp_add<0x121>(x); return x; }
; __device__ __forceinline__ void scan_phase(const Args& a, LAS unsigned char* lds, int tid, int lane, int wave, int G, int bid) {
;     ...
;                     for (int i = 0; i < 16; ++i) {
;                         const f32x4 kk4 = nkk, ak4 = nak, w4 = nw, k4 = nk, r4 = nr; const float vv = vq[i >> 2][i & 3];
;                         { const int nx = (i < 15) ? (i + 1) : (oh < 1 ? 16 : 15); const LAS float* on = opb + nx * SC_STEP;
;                           nkk = *(const LAS f32x4*)(on); nak = *(const LAS f32x4*)(on + 64); nw = *(const LAS f32x4*)(on + 128); nk = *(const LAS f32x4*)(on + 192); nr = *(const LAS f32x4*)(on + 256); }
;                         f32x2 t = Sa * (f32x2){kk4[0], kk4[1]}; t = __builtin_elementwise_fma(Sb, (f32x2){kk4[2], kk4[3]}, t);
;                         float sa = t.x + t.y;
;                         sa = allred16_dpp(sa);
;                         const f32x2 nsa2 = (f32x2){-sa, -sa}, vv2 = (f32x2){vv, vv};
;                         f32x2 ua = vv2 * (f32x2){k4[0], k4[1]}, ub = vv2 * (f32x2){k4[2], k4[3]};
;                         ua = __builtin_elementwise_fma(nsa2, (f32x2){ak4[0], ak4[1]}, ua); ub = __builtin_elementwise_fma(nsa2, (f32x2){ak4[2], ak4[3]}, ub);
;                         Sa = __builtin_elementwise_fma(Sa, (f32x2){w4[0], w4[1]}, ua); Sb = __builtin_elementwise_fma(Sb, (f32x2){w4[2], w4[3]}, ub);
;                         f32x2 yy = Sa * (f32x2){r4[0], r4[1]}; yy = __builtin_elementwise_fma(Sb, (f32x2){r4[2], r4[3]}, yy);
;                         float y = yy.x + yy.y;
;                         y = allred16_dpp(y);
;                         yk = fmaf(wsel[i], y, yk);
	v_pk_mul_f32 v[88:89], v[84:85], v[148:149]
	v_pk_mul_f32 v[90:91], v[84:85], v[72:73]
	v_pk_fma_f32 v[88:89], v[86:87], v[150:151], v[88:89]
	v_pk_fma_f32 v[90:91], v[86:87], v[74:75], v[90:91]
	v_add_f32_e32 v92, v88, v89
	v_add_f32_e32 v118, v90, v91
	v_pk_mul_f32 v[120:121], v[160:161], v[78:79] op_sel:[0,0] op_sel_hi:[1,0]
	v_add_f32_dpp v92, v92, v92 row_ror:8 row_mask:0xf bank_mask:0xf bound_ctrl:1
	v_add_f32_dpp v118, v118, v118 row_ror:8 row_mask:0xf bank_mask:0xf bound_ctrl:1
	v_pk_mul_f32 v[238:239], v[162:163], v[78:79] op_sel:[0,0] op_sel_hi:[1,0]
	v_add_f32_dpp v92, v92, v92 row_ror:4 row_mask:0xf bank_mask:0xf bound_ctrl:1
	v_add_f32_dpp v118, v118, v118 row_ror:4 row_mask:0xf bank_mask:0xf bound_ctrl:1
	v_pk_fma_f32 v[240:241], v[84:85], v[156:157], v[120:121]
	v_add_f32_dpp v92, v92, v92 row_ror:2 row_mask:0xf bank_mask:0xf bound_ctrl:1
	v_add_f32_dpp v118, v118, v118 row_ror:2 row_mask:0xf bank_mask:0xf bound_ctrl:1
	v_pk_fma_f32 v[242:243], v[86:87], v[158:159], v[238:239]
	v_add_f32_dpp v92, v92, v92 row_ror:1 row_mask:0xf bank_mask:0xf bound_ctrl:1
	v_add_f32_dpp v118, v118, v118 row_ror:1 row_mask:0xf bank_mask:0xf bound_ctrl:1
	v_pk_fma_f32 v[84:85], v[92:93], v[152:153], v[240:241] op_sel_hi:[0,1,1] neg_lo:[1,0,0] neg_hi:[1,0,0]
	v_pk_fma_f32 v[86:87], v[92:93], v[154:155], v[242:243] op_sel_hi:[0,1,1] neg_lo:[1,0,0] neg_hi:[1,0,0]
	v_fmac_f32_e32 v244, v129, v118
	ds_read_b128 v[36:39], v101 offset:26880
	ds_read_b128 v[40:43], v101 offset:27136
	ds_read_b128 v[44:47], v101 offset:27392
	ds_read_b128 v[48:51], v101 offset:27648
	ds_read_b128 v[52:55], v101 offset:27904
	s_waitcnt lgkmcnt(6)
	v_pk_mul_f32 v[88:89], v[84:85], v[168:169]
	v_pk_mul_f32 v[90:91], v[84:85], v[164:165]
	v_pk_fma_f32 v[88:89], v[86:87], v[170:171], v[88:89]
	v_pk_fma_f32 v[90:91], v[86:87], v[166:167], v[90:91]
	v_add_f32_e32 v92, v88, v89
	v_add_f32_e32 v118, v90, v91
	v_pk_mul_f32 v[120:121], v[180:181], v[78:79] op_sel:[0,1] op_sel_hi:[1,1]
	v_add_f32_dpp v92, v92, v92 row_ror:8 row_mask:0xf bank_mask:0xf bound_ctrl:1
	v_add_f32_dpp v118, v118, v118 row_ror:8 row_mask:0xf bank_mask:0xf bound_ctrl:1
	v_pk_mul_f32 v[238:239], v[182:183], v[78:79] op_sel:[0,1] op_sel_hi:[1,1]
	v_add_f32_dpp v92, v92, v92 row_ror:4 row_mask:0xf bank_mask:0xf bound_ctrl:1
	v_add_f32_dpp v118, v118, v118 row_ror:4 row_mask:0xf bank_mask:0xf bound_ctrl:1
	v_pk_fma_f32 v[240:241], v[84:85], v[176:177], v[120:121]
	v_add_f32_dpp v92, v92, v92 row_ror:2 row_mask:0xf bank_mask:0xf bound_ctrl:1
	v_add_f32_dpp v118, v118, v118 row_ror:2 row_mask:0xf bank_mask:0xf bound_ctrl:1
	v_pk_fma_f32 v[242:243], v[86:87], v[178:179], v[238:239]
	v_add_f32_dpp v92, v92, v92 row_ror:1 row_mask:0xf bank_mask:0xf bound_ctrl:1
	v_add_f32_dpp v118, v118, v118 row_ror:1 row_mask:0xf bank_mask:0xf bound_ctrl:1
	v_pk_fma_f32 v[84:85], v[92:93], v[172:173], v[240:241] op_sel_hi:[0,1,1] neg_lo:[1,0,0] neg_hi:[1,0,0]
	v_pk_fma_f32 v[86:87], v[92:93], v[174:175], v[242:243] op_sel_hi:[0,1,1] neg_lo:[1,0,0] neg_hi:[1,0,0]
	v_fmac_f32_e32 v244, v131, v118
	ds_read_b128 v[56:59], v101 offset:28224
	ds_read_b128 v[60:63], v101 offset:28480
	ds_read_b128 v[64:67], v101 offset:28736
	ds_read_b128 v[68:71], v101 offset:28992
	ds_read_b128 v[72:75], v101 offset:29248
	s_waitcnt lgkmcnt(5)
	v_pk_mul_f32 v[88:89], v[84:85], v[36:37]
	v_pk_mul_f32 v[90:91], v[84:85], v[184:185]
	v_pk_fma_f32 v[88:89], v[86:87], v[38:39], v[88:89]
	v_pk_fma_f32 v[90:91], v[86:87], v[186:187], v[90:91]
	v_add_f32_e32 v92, v88, v89
	v_add_f32_e32 v118, v90, v91
	v_pk_mul_f32 v[120:121], v[48:49], v[80:81] op_sel:[0,0] op_sel_hi:[1,0]
	v_add_f32_dpp v92, v92, v92 row_ror:8 row_mask:0xf bank_mask:0xf bound_ctrl:1
	v_add_f32_dpp v118, v118, v118 row_ror:8 row_mask:0xf bank_mask:0xf bound_ctrl:1
	v_pk_mul_f32 v[238:239], v[50:51], v[80:81] op_sel:[0,0] op_sel_hi:[1,0]
	v_add_f32_dpp v92, v92, v92 row_ror:4 row_mask:0xf bank_mask:0xf bound_ctrl:1
	v_add_f32_dpp v118, v118, v118 row_ror:4 row_mask:0xf bank_mask:0xf bound_ctrl:1
	v_pk_fma_f32 v[240:241], v[84:85], v[44:45], v[120:121]
	v_add_f32_dpp v92, v92, v92 row_ror:2 row_mask:0xf bank_mask:0xf bound_ctrl:1
	v_add_f32_dpp v118, v118, v118 row_ror:2 row_mask:0xf bank_mask:0xf bound_ctrl:1
	v_pk_fma_f32 v[242:243], v[86:87], v[46:47], v[238:239]
	v_add_f32_dpp v92, v92, v92 row_ror:1 row_mask:0xf bank_mask:0xf bound_ctrl:1
	v_add_f32_dpp v118, v118, v118 row_ror:1 row_mask:0xf bank_mask:0xf bound_ctrl:1
	v_pk_fma_f32 v[84:85], v[92:93], v[40:41], v[240:241] op_sel_hi:[0,1,1] neg_lo:[1,0,0] neg_hi:[1,0,0]
	v_pk_fma_f32 v[86:87], v[92:93], v[42:43], v[242:243] op_sel_hi:[0,1,1] neg_lo:[1,0,0] neg_hi:[1,0,0]
	v_fmac_f32_e32 v244, v132, v118
	ds_read_b128 v[148:151], v101 offset:29568
	ds_read_b128 v[152:155], v101 offset:29824
	ds_read_b128 v[156:159], v101 offset:30080
	ds_read_b128 v[160:163], v101 offset:30336
	ds_read_b128 v[164:167], v101 offset:30592
	s_waitcnt lgkmcnt(5)
; #define LAS __attribute__((address_space(3)))
; __device__ __forceinline__ float allred16_dpp(float x) { x = dpp_add<0x128>(x); x = dpp_add<0x124>(x); x = dpp_add<0x122>(x); x = dpp_add<0x121>(x); return x; }
; __device__ __forceinline__ void scan_phase(const Args& a, LAS unsigned char* lds, int tid, int lane, int wave, int G, int bid) {
;     ...
;                     for (int i = 0; i < 16; ++i) {
;                         const f32x4 kk4 = nkk, ak4 = nak, w4 = nw, k4 = nk, r4 = nr; const float vv = vq[i >> 2][i & 3];
;                         { const int nx = (i < 15) ? (i + 1) : (oh < 1 ? 16 : 15); const LAS float* on = opb + nx * SC_STEP;
;                           nkk = *(const LAS f32x4*)(on); nak = *(const LAS f32x4*)(on + 64); nw = *(const LAS f32x4*)(on + 128); nk = *(const LAS f32x4*)(on + 192); nr = *(const LAS f32x4*)(on + 256); }
;                         f32x2 t = Sa * (f32x2){kk4[0], kk4[1]}; t = __builtin_elementwise_fma(Sb, (f32x2){kk4[2], kk4[3]}, t);
;                         float sa = t.x + t.y;
;                         sa = allred16_dpp(sa);
;                         const f32x2 nsa2 = (f32x2){-sa, -sa}, vv2 = (f32x2){vv, vv};
;                         f32x2 ua = vv2 * (f32x2){k4[0], k4[1]}, ub = vv2 * (f32x2){k4[2], k4[3]};
;                         ua = __builtin_elementwise_fma(nsa2, (f32x2){ak4[0], ak4[1]}, ua); ub = __builtin_elementwise_fma(nsa2, (f32x2){ak4[2], ak4[3]}, ub);
;                         Sa = __builtin_elementwise_fma(Sa, (f32x2){w4[0], w4[1]}, ua); Sb = __builtin_elementwise_fma(Sb, (f32x2){w4[2], w4[3]}, ub);
;                         f32x2 yy = Sa * (f32x2){r4[0], r4[1]}; yy = __builtin_elementwise_fma(Sb, (f32x2){r4[2], r4[3]}, yy);
;                         float y = yy.x + yy.y;
;                         y = allred16_dpp(y);
;                         yk = fmaf(wsel[i], y, yk);
	v_pk_mul_f32 v[88:89], v[84:85], v[56:57]
	v_pk_mul_f32 v[90:91], v[84:85], v[52:53]
	v_pk_fma_f32 v[88:89], v[86:87], v[58:59], v[88:89]
	v_pk_fma_f32 v[90:91], v[86:87], v[54:55], v[90:91]
	v_add_f32_e32 v92, v88, v89
	v_add_f32_e32 v118, v90, v91
	v_pk_mul_f32 v[120:121], v[68:69], v[80:81] op_sel:[0,1] op_sel_hi:[1,1]
	v_add_f32_dpp v92, v92, v92 row_ror:8 row_mask:0xf bank_mask:0xf bound_ctrl:1
	v_add_f32_dpp v118, v118, v118 row_ror:8 row_mask:0xf bank_mask:0xf bound_ctrl:1
	v_pk_mul_f32 v[238:239], v[70:71], v[80:81] op_sel:[0,1] op_sel_hi:[1,1]
	v_add_f32_dpp v92, v92, v92 row_ror:4 row_mask:0xf bank_mask:0xf bound_ctrl:1
	v_add_f32_dpp v118, v118, v118 row_ror:4 row_mask:0xf bank_mask:0xf bound_ctrl:1
	v_pk_fma_f32 v[240:241], v[84:85], v[64:65], v[120:121]
	v_add_f32_dpp v92, v92, v92 row_ror:2 row_mask:0xf bank_mask:0xf bound_ctrl:1
	v_add_f32_dpp v118, v118, v118 row_ror:2 row_mask:0xf bank_mask:0xf bound_ctrl:1
	v_pk_fma_f32 v[242:243], v[86:87], v[66:67], v[238:239]
	v_add_f32_dpp v92, v92, v92 row_ror:1 row_mask:0xf bank_mask:0xf bound_ctrl:1
	v_add_f32_dpp v118, v118, v118 row_ror:1 row_mask:0xf bank_mask:0xf bound_ctrl:1
	v_pk_fma_f32 v[84:85], v[92:93], v[60:61], v[240:241] op_sel_hi:[0,1,1] neg_lo:[1,0,0] neg_hi:[1,0,0]
	v_pk_fma_f32 v[86:87], v[92:93], v[62:63], v[242:243] op_sel_hi:[0,1,1] neg_lo:[1,0,0] neg_hi:[1,0,0]
	v_fmac_f32_e32 v244, v133, v118
	ds_read_b128 v[168:171], v101 offset:30912
	ds_read_b128 v[172:175], v101 offset:31168
	ds_read_b128 v[176:179], v101 offset:31424
	ds_read_b128 v[180:183], v101 offset:31680
	ds_read_b128 v[184:187], v101 offset:31936
	ds_read_b128 v[76:79], v103 offset:1536
	s_waitcnt lgkmcnt(6)
	v_pk_mul_f32 v[88:89], v[84:85], v[148:149]
	v_pk_mul_f32 v[90:91], v[84:85], v[72:73]
	v_pk_fma_f32 v[88:89], v[86:87], v[150:151], v[88:89]
	v_pk_fma_f32 v[90:91], v[86:87], v[74:75], v[90:91]
	v_add_f32_e32 v92, v88, v89
	v_add_f32_e32 v118, v90, v91
	v_pk_mul_f32 v[120:121], v[160:161], v[82:83] op_sel:[0,0] op_sel_hi:[1,0]
	v_add_f32_dpp v92, v92, v92 row_ror:8 row_mask:0xf bank_mask:0xf bound_ctrl:1
	v_add_f32_dpp v118, v118, v118 row_ror:8 row_mask:0xf bank_mask:0xf bound_ctrl:1
	v_pk_mul_f32 v[238:239], v[162:163], v[82:83] op_sel:[0,0] op_sel_hi:[1,0]
	v_add_f32_dpp v92, v92, v92 row_ror:4 row_mask:0xf bank_mask:0xf bound_ctrl:1
	v_add_f32_dpp v118, v118, v118 row_ror:4 row_mask:0xf bank_mask:0xf bound_ctrl:1
	v_pk_fma_f32 v[240:241], v[84:85], v[156:157], v[120:121]
	v_add_f32_dpp v92, v92, v92 row_ror:2 row_mask:0xf bank_mask:0xf bound_ctrl:1
	v_add_f32_dpp v118, v118, v118 row_ror:2 row_mask:0xf bank_mask:0xf bound_ctrl:1
	v_pk_fma_f32 v[242:243], v[86:87], v[158:159], v[238:239]
	v_add_f32_dpp v92, v92, v92 row_ror:1 row_mask:0xf bank_mask:0xf bound_ctrl:1
	v_add_f32_dpp v118, v118, v118 row_ror:1 row_mask:0xf bank_mask:0xf bound_ctrl:1
	v_pk_fma_f32 v[84:85], v[92:93], v[152:153], v[240:241] op_sel_hi:[0,1,1] neg_lo:[1,0,0] neg_hi:[1,0,0]
	v_pk_fma_f32 v[86:87], v[92:93], v[154:155], v[242:243] op_sel_hi:[0,1,1] neg_lo:[1,0,0] neg_hi:[1,0,0]
	v_fmac_f32_e32 v244, v134, v118
	ds_read_b128 v[36:39], v101 offset:32256
	ds_read_b128 v[40:43], v101 offset:32512
	ds_read_b128 v[44:47], v101 offset:32768
	ds_read_b128 v[48:51], v101 offset:33024
	ds_read_b128 v[52:55], v101 offset:33280
	s_waitcnt lgkmcnt(6)
	v_pk_mul_f32 v[88:89], v[84:85], v[168:169]
	v_pk_mul_f32 v[90:91], v[84:85], v[164:165]
	v_pk_fma_f32 v[88:89], v[86:87], v[170:171], v[88:89]
	v_pk_fma_f32 v[90:91], v[86:87], v[166:167], v[90:91]
	v_add_f32_e32 v92, v88, v89
	v_add_f32_e32 v118, v90, v91
	v_pk_mul_f32 v[120:121], v[180:181], v[82:83] op_sel:[0,1] op_sel_hi:[1,1]
	v_add_f32_dpp v92, v92, v92 row_ror:8 row_mask:0xf bank_mask:0xf bound_ctrl:1
	v_add_f32_dpp v118, v118, v118 row_ror:8 row_mask:0xf bank_mask:0xf bound_ctrl:1
	v_pk_mul_f32 v[238:239], v[182:183], v[82:83] op_sel:[0,1] op_sel_hi:[1,1]
	v_add_f32_dpp v92, v92, v92 row_ror:4 row_mask:0xf bank_mask:0xf bound_ctrl:1
	v_add_f32_dpp v118, v118, v118 row_ror:4 row_mask:0xf bank_mask:0xf bound_ctrl:1
	v_pk_fma_f32 v[240:241], v[84:85], v[176:177], v[120:121]
	v_add_f32_dpp v92, v92, v92 row_ror:2 row_mask:0xf bank_mask:0xf bound_ctrl:1
	v_add_f32_dpp v118, v118, v118 row_ror:2 row_mask:0xf bank_mask:0xf bound_ctrl:1
	v_pk_fma_f32 v[242:243], v[86:87], v[178:179], v[238:239]
	v_add_f32_dpp v92, v92, v92 row_ror:1 row_mask:0xf bank_mask:0xf bound_ctrl:1
	v_add_f32_dpp v118, v118, v118 row_ror:1 row_mask:0xf bank_mask:0xf bound_ctrl:1
	v_pk_fma_f32 v[84:85], v[92:93], v[172:173], v[240:241] op_sel_hi:[0,1,1] neg_lo:[1,0,0] neg_hi:[1,0,0]
	v_pk_fma_f32 v[86:87], v[92:93], v[174:175], v[242:243] op_sel_hi:[0,1,1] neg_lo:[1,0,0] neg_hi:[1,0,0]
	v_fmac_f32_e32 v244, v135, v118
	ds_read_b128 v[56:59], v101 offset:33600
	ds_read_b128 v[60:63], v101 offset:33856
	ds_read_b128 v[64:67], v101 offset:34112
	ds_read_b128 v[68:71], v101 offset:34368
	ds_read_b128 v[72:75], v101 offset:34624
	s_waitcnt lgkmcnt(5)
; #define LAS __attribute__((address_space(3)))
; __device__ __forceinline__ float allred16_dpp(float x) { x = dpp_add<0x128>(x); x = dpp_add<0x124>(x); x = dpp_add<0x122>(x); x = dpp_add<0x121>(x); return x; }
; __device__ __forceinline__ void scan_phase(const Args& a, LAS unsigned char* lds, int tid, int lane, int wave, int G, int bid) {
;     ...
;                     for (int i = 0; i < 16; ++i) {
;                         const f32x4 kk4 = nkk, ak4 = nak, w4 = nw, k4 = nk, r4 = nr; const float vv = vq[i >> 2][i & 3];
;                         { const int nx = (i < 15) ? (i + 1) : (oh < 1 ? 16 : 15); const LAS float* on = opb + nx * SC_STEP;
;                           nkk = *(const LAS f32x4*)(on); nak = *(const LAS f32x4*)(on + 64); nw = *(const LAS f32x4*)(on + 128); nk = *(const LAS f32x4*)(on + 192); nr = *(const LAS f32x4*)(on + 256); }
;                         f32x2 t = Sa * (f32x2){kk4[0], kk4[1]}; t = __builtin_elementwise_fma(Sb, (f32x2){kk4[2], kk4[3]}, t);
;                         float sa = t.x + t.y;
;                         sa = allred16_dpp(sa);
;                         const f32x2 nsa2 = (f32x2){-sa, -sa}, vv2 = (f32x2){vv, vv};
;                         f32x2 ua = vv2 * (f32x2){k4[0], k4[1]}, ub = vv2 * (f32x2){k4[2], k4[3]};
;                         ua = __builtin_elementwise_fma(nsa2, (f32x2){ak4[0], ak4[1]}, ua); ub = __builtin_elementwise_fma(nsa2, (f32x2){ak4[2], ak4[3]}, ub);
;                         Sa = __builtin_elementwise_fma(Sa, (f32x2){w4[0], w4[1]}, ua); Sb = __builtin_elementwise_fma(Sb, (f32x2){w4[2], w4[3]}, ub);
;                         f32x2 yy = Sa * (f32x2){r4[0], r4[1]}; yy = __builtin_elementwise_fma(Sb, (f32x2){r4[2], r4[3]}, yy);
;                         float y = yy.x + yy.y;
;                         y = allred16_dpp(y);
;                         yk = fmaf(wsel[i], y, yk);
	v_pk_mul_f32 v[88:89], v[84:85], v[36:37]
	v_pk_mul_f32 v[90:91], v[84:85], v[184:185]
	v_pk_fma_f32 v[88:89], v[86:87], v[38:39], v[88:89]
	v_pk_fma_f32 v[90:91], v[86:87], v[186:187], v[90:91]
	v_add_f32_e32 v92, v88, v89
	v_add_f32_e32 v118, v90, v91
	v_pk_mul_f32 v[120:121], v[48:49], v[76:77] op_sel:[0,0] op_sel_hi:[1,0]
	v_add_f32_dpp v92, v92, v92 row_ror:8 row_mask:0xf bank_mask:0xf bound_ctrl:1
	v_add_f32_dpp v118, v118, v118 row_ror:8 row_mask:0xf bank_mask:0xf bound_ctrl:1
	v_pk_mul_f32 v[238:239], v[50:51], v[76:77] op_sel:[0,0] op_sel_hi:[1,0]
	v_add_f32_dpp v92, v92, v92 row_ror:4 row_mask:0xf bank_mask:0xf bound_ctrl:1
	v_add_f32_dpp v118, v118, v118 row_ror:4 row_mask:0xf bank_mask:0xf bound_ctrl:1
	v_pk_fma_f32 v[240:241], v[84:85], v[44:45], v[120:121]
	v_add_f32_dpp v92, v92, v92 row_ror:2 row_mask:0xf bank_mask:0xf bound_ctrl:1
	v_add_f32_dpp v118, v118, v118 row_ror:2 row_mask:0xf bank_mask:0xf bound_ctrl:1
	v_pk_fma_f32 v[242:243], v[86:87], v[46:47], v[238:239]
	v_add_f32_dpp v92, v92, v92 row_ror:1 row_mask:0xf bank_mask:0xf bound_ctrl:1
	v_add_f32_dpp v118, v118, v118 row_ror:1 row_mask:0xf bank_mask:0xf bound_ctrl:1
	v_pk_fma_f32 v[84:85], v[92:93], v[40:41], v[240:241] op_sel_hi:[0,1,1] neg_lo:[1,0,0] neg_hi:[1,0,0]
	v_pk_fma_f32 v[86:87], v[92:93], v[42:43], v[242:243] op_sel_hi:[0,1,1] neg_lo:[1,0,0] neg_hi:[1,0,0]
	v_fmac_f32_e32 v244, v136, v118
	ds_read_b128 v[148:151], v101 offset:34944
	ds_read_b128 v[152:155], v101 offset:35200
	ds_read_b128 v[156:159], v101 offset:35456
	ds_read_b128 v[160:163], v101 offset:35712
	ds_read_b128 v[164:167], v101 offset:35968
	s_waitcnt lgkmcnt(5)
	v_pk_mul_f32 v[88:89], v[84:85], v[56:57]
	v_pk_mul_f32 v[90:91], v[84:85], v[52:53]
	v_pk_fma_f32 v[88:89], v[86:87], v[58:59], v[88:89]
	v_pk_fma_f32 v[90:91], v[86:87], v[54:55], v[90:91]
	v_add_f32_e32 v92, v88, v89
	v_add_f32_e32 v118, v90, v91
	v_pk_mul_f32 v[120:121], v[68:69], v[76:77] op_sel:[0,1] op_sel_hi:[1,1]
	v_add_f32_dpp v92, v92, v92 row_ror:8 row_mask:0xf bank_mask:0xf bound_ctrl:1
	v_add_f32_dpp v118, v118, v118 row_ror:8 row_mask:0xf bank_mask:0xf bound_ctrl:1
	v_pk_mul_f32 v[238:239], v[70:71], v[76:77] op_sel:[0,1] op_sel_hi:[1,1]
	v_add_f32_dpp v92, v92, v92 row_ror:4 row_mask:0xf bank_mask:0xf bound_ctrl:1
	v_add_f32_dpp v118, v118, v118 row_ror:4 row_mask:0xf bank_mask:0xf bound_ctrl:1
	v_pk_fma_f32 v[240:241], v[84:85], v[64:65], v[120:121]
	v_add_f32_dpp v92, v92, v92 row_ror:2 row_mask:0xf bank_mask:0xf bound_ctrl:1
	v_add_f32_dpp v118, v118, v118 row_ror:2 row_mask:0xf bank_mask:0xf bound_ctrl:1
	v_pk_fma_f32 v[242:243], v[86:87], v[66:67], v[238:239]
	v_add_f32_dpp v92, v92, v92 row_ror:1 row_mask:0xf bank_mask:0xf bound_ctrl:1
	v_add_f32_dpp v118, v118, v118 row_ror:1 row_mask:0xf bank_mask:0xf bound_ctrl:1
	v_pk_fma_f32 v[84:85], v[92:93], v[60:61], v[240:241] op_sel_hi:[0,1,1] neg_lo:[1,0,0] neg_hi:[1,0,0]
	v_pk_fma_f32 v[86:87], v[92:93], v[62:63], v[242:243] op_sel_hi:[0,1,1] neg_lo:[1,0,0] neg_hi:[1,0,0]
	v_fmac_f32_e32 v244, v137, v118
	ds_read_b128 v[168:171], v101 offset:36288
	ds_read_b128 v[172:175], v101 offset:36544
	ds_read_b128 v[176:179], v101 offset:36800
	ds_read_b128 v[180:183], v101 offset:37056
	ds_read_b128 v[184:187], v101 offset:37312
	ds_read_b128 v[80:83], v103 offset:1792
	s_waitcnt lgkmcnt(6)
	v_pk_mul_f32 v[88:89], v[84:85], v[148:149]
	v_pk_mul_f32 v[90:91], v[84:85], v[72:73]
	v_pk_fma_f32 v[88:89], v[86:87], v[150:151], v[88:89]
	v_pk_fma_f32 v[90:91], v[86:87], v[74:75], v[90:91]
	v_add_f32_e32 v92, v88, v89
	v_add_f32_e32 v118, v90, v91
	v_pk_mul_f32 v[120:121], v[160:161], v[78:79] op_sel:[0,0] op_sel_hi:[1,0]
	v_add_f32_dpp v92, v92, v92 row_ror:8 row_mask:0xf bank_mask:0xf bound_ctrl:1
	v_add_f32_dpp v118, v118, v118 row_ror:8 row_mask:0xf bank_mask:0xf bound_ctrl:1
	v_pk_mul_f32 v[238:239], v[162:163], v[78:79] op_sel:[0,0] op_sel_hi:[1,0]
	v_add_f32_dpp v92, v92, v92 row_ror:4 row_mask:0xf bank_mask:0xf bound_ctrl:1
	v_add_f32_dpp v118, v118, v118 row_ror:4 row_mask:0xf bank_mask:0xf bound_ctrl:1
	v_pk_fma_f32 v[240:241], v[84:85], v[156:157], v[120:121]
	v_add_f32_dpp v92, v92, v92 row_ror:2 row_mask:0xf bank_mask:0xf bound_ctrl:1
	v_add_f32_dpp v118, v118, v118 row_ror:2 row_mask:0xf bank_mask:0xf bound_ctrl:1
	v_pk_fma_f32 v[242:243], v[86:87], v[158:159], v[238:239]
	v_add_f32_dpp v92, v92, v92 row_ror:1 row_mask:0xf bank_mask:0xf bound_ctrl:1
	v_add_f32_dpp v118, v118, v118 row_ror:1 row_mask:0xf bank_mask:0xf bound_ctrl:1
	v_pk_fma_f32 v[84:85], v[92:93], v[152:153], v[240:241] op_sel_hi:[0,1,1] neg_lo:[1,0,0] neg_hi:[1,0,0]
	v_pk_fma_f32 v[86:87], v[92:93], v[154:155], v[242:243] op_sel_hi:[0,1,1] neg_lo:[1,0,0] neg_hi:[1,0,0]
	v_fmac_f32_e32 v244, v138, v118
	ds_read_b128 v[36:39], v101 offset:37632
	ds_read_b128 v[40:43], v101 offset:37888
	ds_read_b128 v[44:47], v101 offset:38144
	ds_read_b128 v[48:51], v101 offset:38400
	ds_read_b128 v[52:55], v101 offset:38656
	s_waitcnt lgkmcnt(6)
; #define LAS __attribute__((address_space(3)))
; __device__ __forceinline__ float allred16_dpp(float x) { x = dpp_add<0x128>(x); x = dpp_add<0x124>(x); x = dpp_add<0x122>(x); x = dpp_add<0x121>(x); return x; }
; __device__ __forceinline__ void scan_phase(const Args& a, LAS unsigned char* lds, int tid, int lane, int wave, int G, int bid) {
;     ...
;                     for (int i = 0; i < 16; ++i) {
;                         const f32x4 kk4 = nkk, ak4 = nak, w4 = nw, k4 = nk, r4 = nr; const float vv = vq[i >> 2][i & 3];
;                         { const int nx = (i < 15) ? (i + 1) : (oh < 1 ? 16 : 15); const LAS float* on = opb + nx * SC_STEP;
;                           nkk = *(const LAS f32x4*)(on); nak = *(const LAS f32x4*)(on + 64); nw = *(const LAS f32x4*)(on + 128); nk = *(const LAS f32x4*)(on + 192); nr = *(const LAS f32x4*)(on + 256); }
;                         f32x2 t = Sa * (f32x2){kk4[0], kk4[1]}; t = __builtin_elementwise_fma(Sb, (f32x2){kk4[2], kk4[3]}, t);
;                         float sa = t.x + t.y;
;                         sa = allred16_dpp(sa);
;                         const f32x2 nsa2 = (f32x2){-sa, -sa}, vv2 = (f32x2){vv, vv};
;                         f32x2 ua = vv2 * (f32x2){k4[0], k4[1]}, ub = vv2 * (f32x2){k4[2], k4[3]};
;                         ua = __builtin_elementwise_fma(nsa2, (f32x2){ak4[0], ak4[1]}, ua); ub = __builtin_elementwise_fma(nsa2, (f32x2){ak4[2], ak4[3]}, ub);
;                         Sa = __builtin_elementwise_fma(Sa, (f32x2){w4[0], w4[1]}, ua); Sb = __builtin_elementwise_fma(Sb, (f32x2){w4[2], w4[3]}, ub);
;                         f32x2 yy = Sa * (f32x2){r4[0], r4[1]}; yy = __builtin_elementwise_fma(Sb, (f32x2){r4[2], r4[3]}, yy);
;                         float y = yy.x + yy.y;
;                         y = allred16_dpp(y);
;                         yk = fmaf(wsel[i], y, yk);
	v_pk_mul_f32 v[88:89], v[84:85], v[168:169]
	v_pk_mul_f32 v[90:91], v[84:85], v[164:165]
	v_pk_fma_f32 v[88:89], v[86:87], v[170:171], v[88:89]
	v_pk_fma_f32 v[90:91], v[86:87], v[166:167], v[90:91]
	v_add_f32_e32 v92, v88, v89
	v_add_f32_e32 v118, v90, v91
	v_pk_mul_f32 v[120:121], v[180:181], v[78:79] op_sel:[0,1] op_sel_hi:[1,1]
	v_add_f32_dpp v92, v92, v92 row_ror:8 row_mask:0xf bank_mask:0xf bound_ctrl:1
	v_add_f32_dpp v118, v118, v118 row_ror:8 row_mask:0xf bank_mask:0xf bound_ctrl:1
	v_pk_mul_f32 v[238:239], v[182:183], v[78:79] op_sel:[0,1] op_sel_hi:[1,1]
	v_add_f32_dpp v92, v92, v92 row_ror:4 row_mask:0xf bank_mask:0xf bound_ctrl:1
	v_add_f32_dpp v118, v118, v118 row_ror:4 row_mask:0xf bank_mask:0xf bound_ctrl:1
	v_pk_fma_f32 v[240:241], v[84:85], v[176:177], v[120:121]
	v_add_f32_dpp v92, v92, v92 row_ror:2 row_mask:0xf bank_mask:0xf bound_ctrl:1
	v_add_f32_dpp v118, v118, v118 row_ror:2 row_mask:0xf bank_mask:0xf bound_ctrl:1
	v_pk_fma_f32 v[242:243], v[86:87], v[178:179], v[238:239]
	v_add_f32_dpp v92, v92, v92 row_ror:1 row_mask:0xf bank_mask:0xf bound_ctrl:1
	v_add_f32_dpp v118, v118, v118 row_ror:1 row_mask:0xf bank_mask:0xf bound_ctrl:1
	v_pk_fma_f32 v[84:85], v[92:93], v[172:173], v[240:241] op_sel_hi:[0,1,1] neg_lo:[1,0,0] neg_hi:[1,0,0]
	v_pk_fma_f32 v[86:87], v[92:93], v[174:175], v[242:243] op_sel_hi:[0,1,1] neg_lo:[1,0,0] neg_hi:[1,0,0]
	v_fmac_f32_e32 v244, v139, v118
	ds_read_b128 v[56:59], v101 offset:38976
	ds_read_b128 v[60:63], v101 offset:39232
	ds_read_b128 v[64:67], v101 offset:39488
	ds_read_b128 v[68:71], v101 offset:39744
	ds_read_b128 v[72:75], v101 offset:40000
	s_waitcnt lgkmcnt(5)
	v_pk_mul_f32 v[88:89], v[84:85], v[36:37]
	v_pk_mul_f32 v[90:91], v[84:85], v[184:185]
	v_pk_fma_f32 v[88:89], v[86:87], v[38:39], v[88:89]
	v_pk_fma_f32 v[90:91], v[86:87], v[186:187], v[90:91]
	v_add_f32_e32 v92, v88, v89
	v_add_f32_e32 v118, v90, v91
	v_pk_mul_f32 v[120:121], v[48:49], v[80:81] op_sel:[0,0] op_sel_hi:[1,0]
	v_add_f32_dpp v92, v92, v92 row_ror:8 row_mask:0xf bank_mask:0xf bound_ctrl:1
	v_add_f32_dpp v118, v118, v118 row_ror:8 row_mask:0xf bank_mask:0xf bound_ctrl:1
	v_pk_mul_f32 v[238:239], v[50:51], v[80:81] op_sel:[0,0] op_sel_hi:[1,0]
	v_add_f32_dpp v92, v92, v92 row_ror:4 row_mask:0xf bank_mask:0xf bound_ctrl:1
	v_add_f32_dpp v118, v118, v118 row_ror:4 row_mask:0xf bank_mask:0xf bound_ctrl:1
	v_pk_fma_f32 v[240:241], v[84:85], v[44:45], v[120:121]
	v_add_f32_dpp v92, v92, v92 row_ror:2 row_mask:0xf bank_mask:0xf bound_ctrl:1
	v_add_f32_dpp v118, v118, v118 row_ror:2 row_mask:0xf bank_mask:0xf bound_ctrl:1
	v_pk_fma_f32 v[242:243], v[86:87], v[46:47], v[238:239]
	v_add_f32_dpp v92, v92, v92 row_ror:1 row_mask:0xf bank_mask:0xf bound_ctrl:1
	v_add_f32_dpp v118, v118, v118 row_ror:1 row_mask:0xf bank_mask:0xf bound_ctrl:1
	v_pk_fma_f32 v[84:85], v[92:93], v[40:41], v[240:241] op_sel_hi:[0,1,1] neg_lo:[1,0,0] neg_hi:[1,0,0]
	v_pk_fma_f32 v[86:87], v[92:93], v[42:43], v[242:243] op_sel_hi:[0,1,1] neg_lo:[1,0,0] neg_hi:[1,0,0]
	v_fmac_f32_e32 v244, v140, v118
	ds_read_b128 v[148:151], v101 offset:40320
	ds_read_b128 v[152:155], v101 offset:40576
	ds_read_b128 v[156:159], v101 offset:40832
	ds_read_b128 v[160:163], v101 offset:41088
	ds_read_b128 v[164:167], v101 offset:41344
	s_waitcnt lgkmcnt(5)
	v_pk_mul_f32 v[88:89], v[84:85], v[56:57]
	v_pk_mul_f32 v[90:91], v[84:85], v[52:53]
	v_pk_fma_f32 v[88:89], v[86:87], v[58:59], v[88:89]
	v_pk_fma_f32 v[90:91], v[86:87], v[54:55], v[90:91]
	v_add_f32_e32 v92, v88, v89
	v_add_f32_e32 v118, v90, v91
	v_pk_mul_f32 v[120:121], v[68:69], v[80:81] op_sel:[0,1] op_sel_hi:[1,1]
	v_add_f32_dpp v92, v92, v92 row_ror:8 row_mask:0xf bank_mask:0xf bound_ctrl:1
	v_add_f32_dpp v118, v118, v118 row_ror:8 row_mask:0xf bank_mask:0xf bound_ctrl:1
	v_pk_mul_f32 v[238:239], v[70:71], v[80:81] op_sel:[0,1] op_sel_hi:[1,1]
	v_add_f32_dpp v92, v92, v92 row_ror:4 row_mask:0xf bank_mask:0xf bound_ctrl:1
	v_add_f32_dpp v118, v118, v118 row_ror:4 row_mask:0xf bank_mask:0xf bound_ctrl:1
	v_pk_fma_f32 v[240:241], v[84:85], v[64:65], v[120:121]
	v_add_f32_dpp v92, v92, v92 row_ror:2 row_mask:0xf bank_mask:0xf bound_ctrl:1
	v_add_f32_dpp v118, v118, v118 row_ror:2 row_mask:0xf bank_mask:0xf bound_ctrl:1
	v_pk_fma_f32 v[242:243], v[86:87], v[66:67], v[238:239]
	v_add_f32_dpp v92, v92, v92 row_ror:1 row_mask:0xf bank_mask:0xf bound_ctrl:1
	v_add_f32_dpp v118, v118, v118 row_ror:1 row_mask:0xf bank_mask:0xf bound_ctrl:1
	v_pk_fma_f32 v[84:85], v[92:93], v[60:61], v[240:241] op_sel_hi:[0,1,1] neg_lo:[1,0,0] neg_hi:[1,0,0]
	v_pk_fma_f32 v[86:87], v[92:93], v[62:63], v[242:243] op_sel_hi:[0,1,1] neg_lo:[1,0,0] neg_hi:[1,0,0]
	v_fmac_f32_e32 v244, v141, v118
	ds_read_b128 v[168:171], v101 offset:41664
	ds_read_b128 v[172:175], v101 offset:41920
	ds_read_b128 v[176:179], v101 offset:42176
	ds_read_b128 v[180:183], v101 offset:42432
	ds_read_b128 v[184:187], v101 offset:42688
	s_waitcnt lgkmcnt(5)
; #define LAS __attribute__((address_space(3)))
; __device__ __forceinline__ float allred16_dpp(float x) { x = dpp_add<0x128>(x); x = dpp_add<0x124>(x); x = dpp_add<0x122>(x); x = dpp_add<0x121>(x); return x; }
; __device__ __forceinline__ void scan_phase(const Args& a, LAS unsigned char* lds, int tid, int lane, int wave, int G, int bid) {
;     ...
;                     for (int i = 0; i < 16; ++i) {
;                         const f32x4 kk4 = nkk, ak4 = nak, w4 = nw, k4 = nk, r4 = nr; const float vv = vq[i >> 2][i & 3];
;                         { const int nx = (i < 15) ? (i + 1) : (oh < 1 ? 16 : 15); const LAS float* on = opb + nx * SC_STEP;
;                           nkk = *(const LAS f32x4*)(on); nak = *(const LAS f32x4*)(on + 64); nw = *(const LAS f32x4*)(on + 128); nk = *(const LAS f32x4*)(on + 192); nr = *(const LAS f32x4*)(on + 256); }
;                         f32x2 t = Sa * (f32x2){kk4[0], kk4[1]}; t = __builtin_elementwise_fma(Sb, (f32x2){kk4[2], kk4[3]}, t);
;                         float sa = t.x + t.y;
;                         sa = allred16_dpp(sa);
;                         const f32x2 nsa2 = (f32x2){-sa, -sa}, vv2 = (f32x2){vv, vv};
;                         f32x2 ua = vv2 * (f32x2){k4[0], k4[1]}, ub = vv2 * (f32x2){k4[2], k4[3]};
;                         ua = __builtin_elementwise_fma(nsa2, (f32x2){ak4[0], ak4[1]}, ua); ub = __builtin_elementwise_fma(nsa2, (f32x2){ak4[2], ak4[3]}, ub);
;                         Sa = __builtin_elementwise_fma(Sa, (f32x2){w4[0], w4[1]}, ua); Sb = __builtin_elementwise_fma(Sb, (f32x2){w4[2], w4[3]}, ub);
;                         f32x2 yy = Sa * (f32x2){r4[0], r4[1]}; yy = __builtin_elementwise_fma(Sb, (f32x2){r4[2], r4[3]}, yy);
;                         float y = yy.x + yy.y;
;                         y = allred16_dpp(y);
;                         yk = fmaf(wsel[i], y, yk);
;                     }
;                     YB[(oh * 16 + c) * 16 + row] = yk;
	v_pk_mul_f32 v[88:89], v[84:85], v[148:149]
	v_pk_mul_f32 v[90:91], v[84:85], v[72:73]
	v_pk_fma_f32 v[88:89], v[86:87], v[150:151], v[88:89]
	v_pk_fma_f32 v[90:91], v[86:87], v[74:75], v[90:91]
	v_add_f32_e32 v92, v88, v89
	v_add_f32_e32 v118, v90, v91
	v_pk_mul_f32 v[120:121], v[160:161], v[82:83] op_sel:[0,0] op_sel_hi:[1,0]
	v_add_f32_dpp v92, v92, v92 row_ror:8 row_mask:0xf bank_mask:0xf bound_ctrl:1
	v_add_f32_dpp v118, v118, v118 row_ror:8 row_mask:0xf bank_mask:0xf bound_ctrl:1
	v_pk_mul_f32 v[238:239], v[162:163], v[82:83] op_sel:[0,0] op_sel_hi:[1,0]
	v_add_f32_dpp v92, v92, v92 row_ror:4 row_mask:0xf bank_mask:0xf bound_ctrl:1
	v_add_f32_dpp v118, v118, v118 row_ror:4 row_mask:0xf bank_mask:0xf bound_ctrl:1
	v_pk_fma_f32 v[240:241], v[84:85], v[156:157], v[120:121]
	v_add_f32_dpp v92, v92, v92 row_ror:2 row_mask:0xf bank_mask:0xf bound_ctrl:1
	v_add_f32_dpp v118, v118, v118 row_ror:2 row_mask:0xf bank_mask:0xf bound_ctrl:1
	v_pk_fma_f32 v[242:243], v[86:87], v[158:159], v[238:239]
	v_add_f32_dpp v92, v92, v92 row_ror:1 row_mask:0xf bank_mask:0xf bound_ctrl:1
	v_add_f32_dpp v118, v118, v118 row_ror:1 row_mask:0xf bank_mask:0xf bound_ctrl:1
	v_pk_fma_f32 v[84:85], v[92:93], v[152:153], v[240:241] op_sel_hi:[0,1,1] neg_lo:[1,0,0] neg_hi:[1,0,0]
	v_pk_fma_f32 v[86:87], v[92:93], v[154:155], v[242:243] op_sel_hi:[0,1,1] neg_lo:[1,0,0] neg_hi:[1,0,0]
	v_fmac_f32_e32 v244, v142, v118
	s_waitcnt lgkmcnt(0)
	v_pk_mul_f32 v[88:89], v[84:85], v[168:169]
	v_pk_mul_f32 v[90:91], v[84:85], v[164:165]
	v_pk_fma_f32 v[88:89], v[86:87], v[170:171], v[88:89]
	v_pk_fma_f32 v[90:91], v[86:87], v[166:167], v[90:91]
	v_add_f32_e32 v92, v88, v89
	v_add_f32_e32 v118, v90, v91
	v_pk_mul_f32 v[120:121], v[180:181], v[82:83] op_sel:[0,1] op_sel_hi:[1,1]
	v_add_f32_dpp v92, v92, v92 row_ror:8 row_mask:0xf bank_mask:0xf bound_ctrl:1
	v_add_f32_dpp v118, v118, v118 row_ror:8 row_mask:0xf bank_mask:0xf bound_ctrl:1
	v_pk_mul_f32 v[238:239], v[182:183], v[82:83] op_sel:[0,1] op_sel_hi:[1,1]
	v_add_f32_dpp v92, v92, v92 row_ror:4 row_mask:0xf bank_mask:0xf bound_ctrl:1
	v_add_f32_dpp v118, v118, v118 row_ror:4 row_mask:0xf bank_mask:0xf bound_ctrl:1
	v_pk_fma_f32 v[240:241], v[84:85], v[176:177], v[120:121]
	v_add_f32_dpp v92, v92, v92 row_ror:2 row_mask:0xf bank_mask:0xf bound_ctrl:1
	v_add_f32_dpp v118, v118, v118 row_ror:2 row_mask:0xf bank_mask:0xf bound_ctrl:1
	v_pk_fma_f32 v[242:243], v[86:87], v[178:179], v[238:239]
	v_add_f32_dpp v92, v92, v92 row_ror:1 row_mask:0xf bank_mask:0xf bound_ctrl:1
	v_add_f32_dpp v118, v118, v118 row_ror:1 row_mask:0xf bank_mask:0xf bound_ctrl:1
	v_pk_fma_f32 v[84:85], v[92:93], v[172:173], v[240:241] op_sel_hi:[0,1,1] neg_lo:[1,0,0] neg_hi:[1,0,0]
	v_pk_fma_f32 v[86:87], v[92:93], v[174:175], v[242:243] op_sel_hi:[0,1,1] neg_lo:[1,0,0] neg_hi:[1,0,0]
	v_fmac_f32_e32 v244, v143, v118
	v_pk_mul_f32 v[90:91], v[84:85], v[184:185]
	v_pk_fma_f32 v[90:91], v[86:87], v[186:187], v[90:91]
	v_add_f32_e32 v118, v90, v91
	s_nop 1
	v_add_f32_dpp v118, v118, v118 row_ror:8 row_mask:0xf bank_mask:0xf bound_ctrl:1
	s_nop 1
	v_add_f32_dpp v118, v118, v118 row_ror:4 row_mask:0xf bank_mask:0xf bound_ctrl:1
	s_nop 1
	v_add_f32_dpp v118, v118, v118 row_ror:2 row_mask:0xf bank_mask:0xf bound_ctrl:1
	s_nop 1
	v_add_f32_dpp v118, v118, v118 row_ror:1 row_mask:0xf bank_mask:0xf bound_ctrl:1
	v_fmac_f32_e32 v244, v144, v118
	ds_write_b32 v146, v244 offset:1024

; #define LAS __attribute__((address_space(3)))
; #define NSA_LOAD(KR, VR) do { const int j_ = __builtin_ctzll(lm); lm &= lm - 1; KR = *(const u32x4*)(Ksrc + (size_t)(64 * j_ + key) * 64 + part * 8); VR = *(const u32x4*)(Vsrc + (size_t)(64 * j_ + key) * 64 + part * 8); } while (0)
; template <int MODE> ...
;     ...
;         const int j = __builtin_ctzll(tmask); tmask &= tmask - 1;
;         if (tmask) { NSA_PUT(cur ^ 1); k0 = k1; v0 = v1; if (lm) NSA_LOAD(k1, v1); }
;         const LAS bf16_t* KT = KVB + cur * NSA_BUF; const LAS bf16_t* VT = KT + NSA_KV;
;         const bool act0 = (MODE != 2) || (__ballot(((selm[0] >> j) & 1ull) != 0ull) != 0ull), act1 = (MODE != 2) || (__ballot(((selm[1] >> j) & 1ull) != 0ull) != 0ull);
;         const bool wave_active = act0 || act1;
;         if (wave_active) {
;         constexpr int DM = (MODE == 1) ? 16 : 1;
;         const float sl = slope2 * (float)DM;
;         int dbase[2]; float c0[2];
; #pragma unroll
;         for (int mt = 0; mt < 2; ++mt) { const int sq = 64 * qi + qbase + 16 * mt + fr;
;             dbase[mt] = (MODE == 1) ? sq - 31 - 1024 * j - 64 * fq : sq - 64 * j - 4 * fq;
;             c0[mt] = -slope2 * (float)dbase[mt] - bnd;
;             if (MODE == 2) { if (((selm[mt] >> j) & 1ull) == 0ull) c0[mt] = -1e30f; } }
;         f32x4 st[2][4];
; #pragma unroll
;         for (int nt = 0; nt < 4; ++nt) {
;             const bf16x8 k0 = *(const LAS bf16x8*)(KT + (16 * nt + fr) * 72 + 8 * fq), k1 = *(const LAS bf16x8*)(KT + (16 * nt + fr) * 72 + 32 + 8 * fq);
; #pragma unroll
;             for (int mt = 0; mt < 2; ++mt) { if (!(mt == 0 ? act0 : act1)) continue;
;                 const f32x4 ini = (f32x4){fmaf(sl, (float)(16 * nt), c0[mt]), fmaf(sl, (float)(16 * nt + 1), c0[mt]), fmaf(sl, (float)(16 * nt + 2), c0[mt]), fmaf(sl, (float)(16 * nt + 3), c0[mt])};
;                 f32x4 s = __builtin_amdgcn_mfma_f32_16x16x32_bf16(k0, qf[mt][0], ini, 0, 0, 0);
;                 st[mt][nt] = __builtin_amdgcn_mfma_f32_16x16x32_bf16(k1, qf[mt][1], s, 0, 0, 0);
;             }
;         }
.LBB0_205:
	s_ff1_i32_b64 s23, s[46:47]
	s_lshl_b64 s[48:49], 1, s23
	v_and_b32_e32 v109, s49, v57
	v_and_b32_e32 v108, s48, v56
	s_waitcnt lgkmcnt(0)
	v_and_b32_e32 v119, s49, v59
	v_and_b32_e32 v118, s48, v58
	v_cmp_ne_u64_e64 s[46:47], 0, v[108:109]
	v_cmp_ne_u64_e32 vcc, 0, v[118:119]
	s_or_b64 s[48:49], vcc, s[46:47]
	s_cmp_eq_u64 s[48:49], 0
	s_cbranch_scc1 .LBB0_278
	s_mul_i32 s15, s67, 0x4a00
	v_lshl_or_b32 v108, s23, 6, v128
	s_add_i32 s15, s15, 0
	v_sub_u32_e32 v117, v120, v108
	v_cvt_f32_i32_e32 v116, v117
	v_add3_u32 v112, s15, v165, v188
	ds_read_b128 v[190:193], v112
	ds_read_b128 v[194:197], v112 offset:64
	v_add3_u32 v246, s15, v166, v188
	ds_read_b128 v[210:213], v246
	ds_read_b128 v[214:217], v246 offset:64
	v_add3_u32 v247, s15, v167, v188
	ds_read_b128 v[218:221], v247
	ds_read_b128 v[222:225], v247 offset:64
	v_add3_u32 v248, s15, v173, v188
	ds_read_b128 v[238:241], v248
	ds_read_b128 v[242:245], v248 offset:64
	s_cmp_lg_u64 s[46:47], 0
	v_fma_f32 v116, -v134, v116, -v182
	s_cselect_b64 s[62:63], -1, 0
	s_cmp_eq_u64 s[46:47], 0
	v_cndmask_b32_e64 v116, v235, v116, s[46:47]
	s_cbranch_scc1 .LBB0_208
	v_fma_f32 v88, 0, v134, v116
	v_add_f32_e32 v89, v134, v116
	v_pk_fma_f32 v[90:91], v[146:147], s[4:5], v[116:117] op_sel_hi:[1,1,0]
	s_waitcnt lgkmcnt(7)
	s_nop 0
	v_mfma_f32_16x16x32_bf16 v[88:91], v[190:193], v[8:11], v[88:91]
	s_waitcnt lgkmcnt(6)
	v_mfma_f32_16x16x32_bf16 v[88:91], v[194:197], v[12:15], v[88:91]
.LBB0_208:
	v_add_u32_e32 v124, 16, v117
	v_cvt_f32_i32_e32 v124, v124
	s_cmp_lg_u64 vcc, 0
	s_cselect_b64 s[60:61], -1, 0
	s_cmp_eq_u64 vcc, 0
	v_fma_f32 v124, -v134, v124, -v182
	v_cmp_ne_u64_e32 vcc, 0, v[118:119]
	s_nop 1
	v_cndmask_b32_e32 v118, v235, v124, vcc
	s_cbranch_scc1 .LBB0_210
	v_fma_f32 v72, 0, v134, v118
	v_add_f32_e32 v73, v134, v118
	v_pk_fma_f32 v[74:75], v[146:147], s[4:5], v[118:119] op_sel_hi:[1,1,0]
	s_waitcnt lgkmcnt(7)
	s_nop 0
	v_mfma_f32_16x16x32_bf16 v[72:75], v[190:193], v[16:19], v[72:75]
	s_waitcnt lgkmcnt(6)
	v_mfma_f32_16x16x32_bf16 v[72:75], v[194:197], v[20:23], v[72:75]
.LBB0_210:
	v_cndmask_b32_e64 v119, 0, 1, s[62:63]
	v_cmp_ne_u32_e64 s[46:47], 1, v119
	s_andn2_b64 vcc, exec, s[62:63]
	s_cbranch_vccnz .LBB0_212
	v_mov_b32_e32 v135, v134
	v_pk_fma_f32 v[98:99], v[134:135], s[12:13], v[116:117] op_sel_hi:[1,1,0]
	v_pk_fma_f32 v[96:97], v[148:149], s[6:7], v[116:117] op_sel_hi:[1,1,0]
	s_waitcnt lgkmcnt(5)
	s_nop 0
	v_mfma_f32_16x16x32_bf16 v[96:99], v[210:213], v[8:11], v[96:99]
	s_waitcnt lgkmcnt(4)
	v_mfma_f32_16x16x32_bf16 v[96:99], v[214:217], v[12:15], v[96:99]
.LBB0_212:
	v_cndmask_b32_e64 v119, 0, 1, s[60:61]
	v_cmp_ne_u32_e64 s[48:49], 1, v119
	s_andn2_b64 vcc, exec, s[60:61]
	s_cbranch_vccnz .LBB0_214
	v_mov_b32_e32 v135, v134
	v_pk_fma_f32 v[82:83], v[134:135], s[12:13], v[118:119] op_sel_hi:[1,1,0]
	v_pk_fma_f32 v[80:81], v[148:149], s[6:7], v[118:119] op_sel_hi:[1,1,0]
	s_waitcnt lgkmcnt(5)
	s_nop 0
	v_mfma_f32_16x16x32_bf16 v[80:83], v[210:213], v[16:19], v[80:83]
	s_waitcnt lgkmcnt(4)
	v_mfma_f32_16x16x32_bf16 v[80:83], v[214:217], v[20:23], v[80:83]
.LBB0_214:
	s_and_b64 vcc, exec, s[46:47]
	s_cbranch_vccnz .LBB0_216
	v_mov_b32_e32 v135, v134
	v_pk_fma_f32 v[94:95], v[134:135], s[0:1], v[116:117] op_sel_hi:[1,1,0]
	v_pk_fma_f32 v[92:93], v[148:149], s[2:3], v[116:117] op_sel_hi:[1,1,0]
	s_waitcnt lgkmcnt(3)
	s_nop 0
	v_mfma_f32_16x16x32_bf16 v[92:95], v[218:221], v[8:11], v[92:95]
	s_waitcnt lgkmcnt(2)
	v_mfma_f32_16x16x32_bf16 v[92:95], v[222:225], v[12:15], v[92:95]
.LBB0_216:
	s_and_b64 vcc, exec, s[48:49]
	s_cbranch_vccnz .LBB0_218
	v_mov_b32_e32 v135, v134
	v_pk_fma_f32 v[78:79], v[134:135], s[0:1], v[118:119] op_sel_hi:[1,1,0]
	v_pk_fma_f32 v[76:77], v[148:149], s[2:3], v[118:119] op_sel_hi:[1,1,0]
	s_waitcnt lgkmcnt(3)
	s_nop 0
	v_mfma_f32_16x16x32_bf16 v[76:79], v[218:221], v[16:19], v[76:79]
	s_waitcnt lgkmcnt(2)
	v_mfma_f32_16x16x32_bf16 v[76:79], v[222:225], v[20:23], v[76:79]
.LBB0_218:
	s_and_b64 vcc, exec, s[46:47]
	s_cbranch_vccnz .LBB0_220
	v_mov_b32_e32 v135, v134
	v_pk_fma_f32 v[86:87], v[134:135], s[88:89], v[116:117] op_sel_hi:[1,1,0]
	v_pk_fma_f32 v[84:85], v[148:149], s[92:93], v[116:117] op_sel_hi:[1,1,0]
	s_waitcnt lgkmcnt(1)
	s_nop 0
	v_mfma_f32_16x16x32_bf16 v[84:87], v[238:241], v[8:11], v[84:87]
	s_waitcnt lgkmcnt(0)
	v_mfma_f32_16x16x32_bf16 v[84:87], v[242:245], v[12:15], v[84:87]
.LBB0_220:
	s_and_b64 vcc, exec, s[48:49]
	s_cbranch_vccnz .LBB0_222
	v_mov_b32_e32 v135, v134
	v_pk_fma_f32 v[70:71], v[134:135], s[88:89], v[118:119] op_sel_hi:[1,1,0]
	v_pk_fma_f32 v[68:69], v[148:149], s[92:93], v[118:119] op_sel_hi:[1,1,0]
	s_waitcnt lgkmcnt(1)
	s_nop 0
	v_mfma_f32_16x16x32_bf16 v[68:71], v[238:241], v[16:19], v[68:71]
	s_waitcnt lgkmcnt(0)
	v_mfma_f32_16x16x32_bf16 v[68:71], v[242:245], v[20:23], v[68:71]

; #define LAS __attribute__((address_space(3)))
; __device__ __forceinline__ unsigned pk2(float lo, float hi) { return pg8::cvt_pk_bf16(lo, hi); }
; template <int MODE> ...
;     ...
;         for (int ks = 0; ks < 2; ++ks) {
;             bf16x8 pb[2];
; #pragma unroll
;             for (int mt = 0; mt < 2; ++mt) { if (!(mt == 0 ? act0 : act1)) { pb[mt] = (bf16x8){0, 0, 0, 0, 0, 0, 0, 0}; continue; } u32x4 w; const f32x4 pa = st[mt][2 * ks], pc = st[mt][2 * ks + 1];
;                 w.x = pk2(pa[0], pa[1]); w.y = pk2(pa[2], pa[3]); w.z = pk2(pc[0], pc[1]); w.w = pk2(pc[2], pc[3]); pb[mt] = __builtin_bit_cast(bf16x8, w); }
; #pragma unroll
;             for (int dt = 0; dt < 4; ++dt) {
;                 const u32x2 lo = *(const LAS u32x2*)(VT + (16 * dt + fr) * NSA_VS + 32 * ks + 4 * fq), hi = *(const LAS u32x2*)(VT + (16 * dt + fr) * NSA_VS + 32 * ks + 16 + 4 * fq);
;                 const bf16x8 vf = __builtin_bit_cast(bf16x8, ((u32x4){lo.x, lo.y, hi.x, hi.y}));
; #pragma unroll
;                 for (int mt = 0; mt < 2; ++mt) { if (mt == 0 ? act0 : act1) o[mt][dt] = __builtin_amdgcn_mfma_f32_16x16x32_bf16(vf, pb[mt], o[mt][dt], 0, 0, 0); }
;             }
;         }
.LBB0_240:
	v_add3_u32 v116, s15, v168, v154
	v_add_u32_e32 v124, 0x2000, v116
	v_add3_u32 v116, s15, v169, v154
	v_add_u32_e32 v135, 0x2000, v116
	v_add3_u32 v116, s15, v170, v154
	v_add_u32_e32 v137, 0x2000, v116
	v_add3_u32 v116, s15, v174, v154
	v_add_u32_e32 v155, 0x2000, v116
	ds_read2_b64 v[190:193], v124 offset0:128 offset1:132
	ds_read2_b64 v[194:197], v135 offset0:128 offset1:132
	ds_read2_b64 v[210:213], v137 offset0:128 offset1:132
	ds_read2_b64 v[214:217], v155 offset0:128 offset1:132
	ds_read2_b64 v[218:221], v124 offset0:136 offset1:140
	ds_read2_b64 v[222:225], v135 offset0:136 offset1:140
	ds_read2_b64 v[238:241], v137 offset0:136 offset1:140
	ds_read2_b64 v[242:245], v155 offset0:136 offset1:140
	s_and_b64 vcc, exec, s[46:47]
	s_cbranch_vccnz .LBB0_242
	s_waitcnt lgkmcnt(7)
	v_mfma_f32_16x16x32_bf16 v[52:55], v[190:193], v[108:111], v[52:55]
.LBB0_242:
	s_and_b64 vcc, exec, s[48:49]
	s_cbranch_vccnz .LBB0_244
	s_waitcnt lgkmcnt(7)
	v_mfma_f32_16x16x32_bf16 v[36:39], v[190:193], v[112:115], v[36:39]
.LBB0_244:
	s_and_b64 vcc, exec, s[46:47]
	s_cbranch_vccnz .LBB0_246
	s_waitcnt lgkmcnt(6)
	v_mfma_f32_16x16x32_bf16 v[48:51], v[194:197], v[108:111], v[48:51]
.LBB0_246:
	s_and_b64 vcc, exec, s[48:49]
	s_cbranch_vccnz .LBB0_248
	s_waitcnt lgkmcnt(6)
	v_mfma_f32_16x16x32_bf16 v[32:35], v[194:197], v[112:115], v[32:35]
.LBB0_248:
	s_and_b64 vcc, exec, s[46:47]
	s_cbranch_vccnz .LBB0_250
	s_waitcnt lgkmcnt(5)
	v_mfma_f32_16x16x32_bf16 v[44:47], v[210:213], v[108:111], v[44:47]
.LBB0_250:
	s_and_b64 vcc, exec, s[48:49]
	s_cbranch_vccnz .LBB0_252
	s_waitcnt lgkmcnt(5)
	v_mfma_f32_16x16x32_bf16 v[28:31], v[210:213], v[112:115], v[28:31]
.LBB0_252:
	s_and_b64 vcc, exec, s[46:47]
	s_cbranch_vccnz .LBB0_254
	s_waitcnt lgkmcnt(4)
	v_mfma_f32_16x16x32_bf16 v[40:43], v[214:217], v[108:111], v[40:43]
.LBB0_254:
	s_and_b64 vcc, exec, s[48:49]
	s_cbranch_vccnz .LBB0_256
	s_waitcnt lgkmcnt(4)
	v_mfma_f32_16x16x32_bf16 v[24:27], v[214:217], v[112:115], v[24:27]

; #define LAS __attribute__((address_space(3)))
; __device__ __forceinline__ unsigned pk2(float lo, float hi) { return pg8::cvt_pk_bf16(lo, hi); }
; template <int MODE> ...
;     ...
;         for (int ks = 0; ks < 2; ++ks) {
;             bf16x8 pb[2];
; #pragma unroll
;             for (int mt = 0; mt < 2; ++mt) { if (!(mt == 0 ? act0 : act1)) { pb[mt] = (bf16x8){0, 0, 0, 0, 0, 0, 0, 0}; continue; } u32x4 w; const f32x4 pa = st[mt][2 * ks], pc = st[mt][2 * ks + 1];
;                 w.x = pk2(pa[0], pa[1]); w.y = pk2(pa[2], pa[3]); w.z = pk2(pc[0], pc[1]); w.w = pk2(pc[2], pc[3]); pb[mt] = __builtin_bit_cast(bf16x8, w); }
; #pragma unroll
;             for (int dt = 0; dt < 4; ++dt) {
;                 const u32x2 lo = *(const LAS u32x2*)(VT + (16 * dt + fr) * NSA_VS + 32 * ks + 4 * fq), hi = *(const LAS u32x2*)(VT + (16 * dt + fr) * NSA_VS + 32 * ks + 16 + 4 * fq);
;                 const bf16x8 vf = __builtin_bit_cast(bf16x8, ((u32x4){lo.x, lo.y, hi.x, hi.y}));
; #pragma unroll
;                 for (int mt = 0; mt < 2; ++mt) { if (mt == 0 ? act0 : act1) o[mt][dt] = __builtin_amdgcn_mfma_f32_16x16x32_bf16(vf, pb[mt], o[mt][dt], 0, 0, 0); }
;             }
;         }
.LBB0_262:
	s_and_b64 vcc, exec, s[46:47]
	s_cbranch_vccnz .LBB0_264
	s_waitcnt lgkmcnt(3)
	v_mfma_f32_16x16x32_bf16 v[52:55], v[218:221], v[108:111], v[52:55]
.LBB0_264:
	s_and_b64 vcc, exec, s[48:49]
	s_cbranch_vccnz .LBB0_266
	s_waitcnt lgkmcnt(3)
	v_mfma_f32_16x16x32_bf16 v[36:39], v[218:221], v[112:115], v[36:39]
.LBB0_266:
	s_and_b64 vcc, exec, s[46:47]
	s_cbranch_vccnz .LBB0_268
	s_waitcnt lgkmcnt(2)
	v_mfma_f32_16x16x32_bf16 v[48:51], v[222:225], v[108:111], v[48:51]
.LBB0_268:
	s_and_b64 vcc, exec, s[48:49]
	s_cbranch_vccnz .LBB0_270
	s_waitcnt lgkmcnt(2)
	v_mfma_f32_16x16x32_bf16 v[32:35], v[222:225], v[112:115], v[32:35]
.LBB0_270:
	s_and_b64 vcc, exec, s[46:47]
	s_cbranch_vccnz .LBB0_272
	s_waitcnt lgkmcnt(1)
	v_mfma_f32_16x16x32_bf16 v[44:47], v[238:241], v[108:111], v[44:47]
.LBB0_272:
	s_and_b64 vcc, exec, s[48:49]
	s_cbranch_vccnz .LBB0_274
	s_waitcnt lgkmcnt(1)
	v_mfma_f32_16x16x32_bf16 v[28:31], v[238:241], v[112:115], v[28:31]
.LBB0_274:
	s_and_b64 vcc, exec, s[46:47]
	s_cbranch_vccnz .LBB0_276
	s_waitcnt lgkmcnt(0)
	v_mfma_f32_16x16x32_bf16 v[40:43], v[242:245], v[108:111], v[40:43]
.LBB0_276:
	s_and_b64 vcc, exec, s[48:49]
	s_cbranch_vccnz .LBB0_278
	s_waitcnt lgkmcnt(0)
	v_mfma_f32_16x16x32_bf16 v[24:27], v[242:245], v[112:115], v[24:27]
